# v11 + G34/G2 epilogues: per-row scale loads hoisted, store-draining waits only on paths that issued a load
# speedup vs baseline: 1.0057x; 1.0057x over previous
; #define GAS __attribute__((address_space(1)))
; __device__ __forceinline__ u32x4 pack8(const f32x4& a, const f32x4& b) { u32x4 w; w.x = cvt_pk_bf16(a[0], a[1]); w.y = cvt_pk_bf16(a[2], a[3]); w.z = cvt_pk_bf16(b[0], b[1]); w.w = cvt_pk_bf16(b[2], b[3]); return w; }
; #define GAS __attribute__((address_space(1)))
;     __device__ __forceinline__ void operator()(const f32x4 (&acc)[2][2][4][2], const Unit& u, int wr, int wc, int fr_, int fq_) const {
;     ...
;                 for (int m = 0; m < 4; ++m) { const int row = row0 + ai * HALF + m * 16;
;                     float sc = 1.f; if constexpr (MODE == EP_Q || MODE == EP_KV) sc = ((const GAS float*)rs)[row]; if constexpr (MODE == EP_GATE) { if (u.pn < 12) sc = ((const GAS float*)rs2)[row]; }
;                     if constexpr (MODE == EP_G2) { if (kind == 0) sc = ((const GAS float*)rs)[row]; else if (kind == 1) sc = ((const GAS float*)rs2)[row]; }
; #pragma unroll
;                     for (int bj = 0; bj < 2; ++bj) { const int col = colt + bj * HALF; f32x4 v0 = acc[ai][bj][m][0] * sc, v1 = acc[ai][bj][m][1] * sc;
;                         if constexpr (MODE == EP_STORE) { *(GAS u32x4*)(O + (size_t)row * ldc + col) = pack8(v0, v1); }
;                         else if constexpr (MODE == EP_BR) {
;                             ((GAS u32x4*)O)[((size_t)((((pm * 12 + u.pn) * 2 + ai) * 4 + m) * 2 + bj)) * 512 + wv_ * 64 + ln_] = pack8(v0, v1); }
;                         else if constexpr (MODE == EP_Q) { *(GAS u32x4*)(O + (size_t)row * ldc + col) = pack8(v0, v1); }
;                         else if constexpr (MODE == EP_G2) {
;                             if (kind == 0) *(GAS u32x4*)(O + (size_t)row * QW + col) = pack8(v0, v1);
;                             else if (kind == 1) { if (col < 512) *(GAS u32x4*)(O2 + (size_t)row * QW + (col >> 6) * QKD + (col & 63)) = pack8(v0, v1); else *(GAS u32x4*)(O3 + (size_t)row * VW + (col - 512)) = pack8(v0, v1); }
.LBB0_510:
	v_mbcnt_lo_u32_b32 v130, -1, v130
	s_lshl_b32 s42, s0, 8
	v_mbcnt_hi_u32_b32 v130, -1, v130
	s_add_i32 s42, s42, s87
	v_and_or_b32 v156, v130, 15, s42
	v_cndmask_b32_e64 v131, 0, 1, s[46:47]
	v_ashrrev_i32_e32 v157, 31, v156
	v_cmp_ne_u32_e64 s[42:43], 1, v131
	s_andn2_b64 vcc, exec, s[46:47]
	v_mov_b32_e32 v164, 1.0
	s_cbranch_vccnz .LBB0_512
	s_and_b64 s[46:47], exec, s[58:59]
	s_cselect_b32 s46, s84, s86
	s_cselect_b32 s47, s83, s85
	v_mov_b32_e32 v132, s47
	v_mov_b32_e32 v133, s46
	v_lshl_add_u64 v[132:133], v[156:157], 2, v[132:133]
	global_load_dword v164, v[132:133], off
	global_load_dword v196, v[132:133], off offset:64
	global_load_dword v197, v[132:133], off offset:128
	global_load_dword v198, v[132:133], off offset:192
	global_load_dword v199, v[132:133], off offset:512
	global_load_dword v200, v[132:133], off offset:576
	global_load_dword v201, v[132:133], off offset:640
	global_load_dword v202, v[132:133], off offset:704
	s_waitcnt vmcnt(0)
.LBB0_512:
	v_ashrrev_i32_e32 v130, 1, v130
	v_and_b32_e32 v130, -8, v130
	v_add_u32_e32 v130, s88, v130
	v_mad_i64_i32 v[158:159], s[46:47], v156, s95, 0
	v_lshl_add_u32 v154, s37, 8, v130
	v_and_b32_e32 v139, 56, v130
	v_lshlrev_b64 v[160:161], 10, v[156:157]
	v_pk_mul_f32 v[168:169], v[102:103], v[164:165] op_sel_hi:[1,0]
	v_pk_mul_f32 v[172:173], v[100:101], v[164:165] op_sel_hi:[1,0]
	v_pk_mul_f32 v[166:167], v[94:95], v[164:165] op_sel_hi:[1,0]
	v_pk_mul_f32 v[170:171], v[92:93], v[164:165] op_sel_hi:[1,0]
	s_mov_b64 s[46:47], -1
	s_and_b64 vcc, exec, s[44:45]
	s_cbranch_vccz .LBB0_522
	s_and_b64 vcc, exec, s[60:61]
	s_cbranch_vccz .LBB0_515
	v_lshl_add_u64 v[162:163], s[28:29], 0, v[160:161]
	v_ashrrev_i32_e32 v155, 31, v154
	v_cvt_pk_bf16_f32 v130, v172, v173
	v_cvt_pk_bf16_f32 v131, v168, v169
	v_cvt_pk_bf16_f32 v132, v170, v171
	v_cvt_pk_bf16_f32 v133, v166, v167
	v_lshl_add_u64 v[192:193], v[154:155], 1, v[162:163]
	s_mov_b64 s[46:47], 0

; #define GAS __attribute__((address_space(1)))
; __device__ __forceinline__ u32x4 pack8(const f32x4& a, const f32x4& b) { u32x4 w; w.x = cvt_pk_bf16(a[0], a[1]); w.y = cvt_pk_bf16(a[2], a[3]); w.z = cvt_pk_bf16(b[0], b[1]); w.w = cvt_pk_bf16(b[2], b[3]); return w; }
; #define GAS __attribute__((address_space(1)))
;     __device__ __forceinline__ void operator()(const f32x4 (&acc)[2][2][4][2], const Unit& u, int wr, int wc, int fr_, int fq_) const {
;     ...
;                 for (int m = 0; m < 4; ++m) { const int row = row0 + ai * HALF + m * 16;
;                     float sc = 1.f; if constexpr (MODE == EP_Q || MODE == EP_KV) sc = ((const GAS float*)rs)[row]; if constexpr (MODE == EP_GATE) { if (u.pn < 12) sc = ((const GAS float*)rs2)[row]; }
;                     if constexpr (MODE == EP_G2) { if (kind == 0) sc = ((const GAS float*)rs)[row]; else if (kind == 1) sc = ((const GAS float*)rs2)[row]; }
; #pragma unroll
;                     for (int bj = 0; bj < 2; ++bj) { const int col = colt + bj * HALF; f32x4 v0 = acc[ai][bj][m][0] * sc, v1 = acc[ai][bj][m][1] * sc;
;                         if constexpr (MODE == EP_STORE) { *(GAS u32x4*)(O + (size_t)row * ldc + col) = pack8(v0, v1); }
;                         else if constexpr (MODE == EP_BR) {
;                             ((GAS u32x4*)O)[((size_t)((((pm * 12 + u.pn) * 2 + ai) * 4 + m) * 2 + bj)) * 512 + wv_ * 64 + ln_] = pack8(v0, v1); }
;                         else if constexpr (MODE == EP_Q) { *(GAS u32x4*)(O + (size_t)row * ldc + col) = pack8(v0, v1); }
;                         else if constexpr (MODE == EP_G2) {
;                             if (kind == 0) *(GAS u32x4*)(O + (size_t)row * QW + col) = pack8(v0, v1);
;                             else if (kind == 1) { if (col < 512) *(GAS u32x4*)(O2 + (size_t)row * QW + (col >> 6) * QKD + (col & 63)) = pack8(v0, v1); else *(GAS u32x4*)(O3 + (size_t)row * VW + (col - 512)) = pack8(v0, v1); }
;                             else *(GAS u32x4*)(O4 + (size_t)row * 512 + col) = pack8(v0, v1); }
.LBB0_535:
	s_and_b64 s[60:61], exec, s[58:59]
	s_cselect_b32 s37, s84, s86
	s_cselect_b32 s53, s83, s85
	v_mov_b32_e32 v130, s53
	v_mov_b32_e32 v131, s37
	v_lshl_add_u64 v[130:131], v[156:157], 2, v[130:131]
	s_nop 1
	v_mov_b32_e32 v164, v196
.LBB0_536:
	s_nop 0
	v_or_b32_e32 v130, 16, v156
	v_ashrrev_i32_e32 v131, 31, v130
	v_mad_i64_i32 v[158:159], s[60:61], v130, s95, 0
	v_lshlrev_b64 v[160:161], 10, v[130:131]
	v_pk_mul_f32 v[168:169], v[86:87], v[164:165] op_sel_hi:[1,0]
	v_pk_mul_f32 v[172:173], v[84:85], v[164:165] op_sel_hi:[1,0]
	v_pk_mul_f32 v[166:167], v[82:83], v[164:165] op_sel_hi:[1,0]
	v_pk_mul_f32 v[170:171], v[80:81], v[164:165] op_sel_hi:[1,0]
	s_and_b64 vcc, exec, s[46:47]
	s_mov_b64 s[60:61], -1
	s_cbranch_vccnz .LBB0_546
	s_and_b64 vcc, exec, s[44:45]
	s_cbranch_vccnz .LBB0_539
	v_lshl_add_u64 v[162:163], s[28:29], 0, v[160:161]
	v_lshl_add_u64 v[192:193], v[154:155], 1, v[162:163]
	s_mov_b64 s[60:61], 0
	v_cvt_pk_bf16_f32 v130, v172, v173
	v_cvt_pk_bf16_f32 v131, v168, v169
	v_cvt_pk_bf16_f32 v132, v170, v171
	v_cvt_pk_bf16_f32 v133, v166, v167

; #define GAS __attribute__((address_space(1)))
; __device__ __forceinline__ u32x4 pack8(const f32x4& a, const f32x4& b) { u32x4 w; w.x = cvt_pk_bf16(a[0], a[1]); w.y = cvt_pk_bf16(a[2], a[3]); w.z = cvt_pk_bf16(b[0], b[1]); w.w = cvt_pk_bf16(b[2], b[3]); return w; }
; #define GAS __attribute__((address_space(1)))
;     __device__ __forceinline__ void operator()(const f32x4 (&acc)[2][2][4][2], const Unit& u, int wr, int wc, int fr_, int fq_) const {
;     ...
;                 for (int m = 0; m < 4; ++m) { const int row = row0 + ai * HALF + m * 16;
;                     float sc = 1.f; if constexpr (MODE == EP_Q || MODE == EP_KV) sc = ((const GAS float*)rs)[row]; if constexpr (MODE == EP_GATE) { if (u.pn < 12) sc = ((const GAS float*)rs2)[row]; }
;                     if constexpr (MODE == EP_G2) { if (kind == 0) sc = ((const GAS float*)rs)[row]; else if (kind == 1) sc = ((const GAS float*)rs2)[row]; }
; #pragma unroll
;                     for (int bj = 0; bj < 2; ++bj) { const int col = colt + bj * HALF; f32x4 v0 = acc[ai][bj][m][0] * sc, v1 = acc[ai][bj][m][1] * sc;
;                         if constexpr (MODE == EP_STORE) { *(GAS u32x4*)(O + (size_t)row * ldc + col) = pack8(v0, v1); }
;                         else if constexpr (MODE == EP_BR) {
;                             ((GAS u32x4*)O)[((size_t)((((pm * 12 + u.pn) * 2 + ai) * 4 + m) * 2 + bj)) * 512 + wv_ * 64 + ln_] = pack8(v0, v1); }
;                         else if constexpr (MODE == EP_Q) { *(GAS u32x4*)(O + (size_t)row * ldc + col) = pack8(v0, v1); }
;                         else if constexpr (MODE == EP_G2) {
;                             if (kind == 0) *(GAS u32x4*)(O + (size_t)row * QW + col) = pack8(v0, v1);
;                             else if (kind == 1) { if (col < 512) *(GAS u32x4*)(O2 + (size_t)row * QW + (col >> 6) * QKD + (col & 63)) = pack8(v0, v1); else *(GAS u32x4*)(O3 + (size_t)row * VW + (col - 512)) = pack8(v0, v1); }
;                             else *(GAS u32x4*)(O4 + (size_t)row * 512 + col) = pack8(v0, v1); }
.LBB0_559:
	s_and_b64 s[60:61], exec, s[58:59]
	s_cselect_b32 s37, s84, s86
	s_cselect_b32 s53, s83, s85
	v_mov_b32_e32 v130, s53
	v_mov_b32_e32 v131, s37
	v_lshl_add_u64 v[130:131], v[156:157], 2, v[130:131]
	s_nop 1
	v_mov_b32_e32 v164, v197
.LBB0_560:
	s_nop 0
	v_or_b32_e32 v130, 32, v156
	v_ashrrev_i32_e32 v131, 31, v130
	v_mad_i64_i32 v[158:159], s[60:61], v130, s95, 0
	v_lshlrev_b64 v[160:161], 10, v[130:131]
	v_pk_mul_f32 v[168:169], v[78:79], v[164:165] op_sel_hi:[1,0]
	v_pk_mul_f32 v[172:173], v[76:77], v[164:165] op_sel_hi:[1,0]
	v_pk_mul_f32 v[166:167], v[74:75], v[164:165] op_sel_hi:[1,0]
	v_pk_mul_f32 v[170:171], v[72:73], v[164:165] op_sel_hi:[1,0]
	s_and_b64 vcc, exec, s[46:47]
	s_mov_b64 s[60:61], -1
	s_cbranch_vccnz .LBB0_570
	s_and_b64 vcc, exec, s[44:45]
	s_cbranch_vccnz .LBB0_563
	v_lshl_add_u64 v[162:163], s[28:29], 0, v[160:161]
	v_lshl_add_u64 v[192:193], v[154:155], 1, v[162:163]
	s_mov_b64 s[60:61], 0
	v_cvt_pk_bf16_f32 v130, v172, v173
	v_cvt_pk_bf16_f32 v131, v168, v169
	v_cvt_pk_bf16_f32 v132, v170, v171
	v_cvt_pk_bf16_f32 v133, v166, v167

; #define GAS __attribute__((address_space(1)))
; __device__ __forceinline__ u32x4 pack8(const f32x4& a, const f32x4& b) { u32x4 w; w.x = cvt_pk_bf16(a[0], a[1]); w.y = cvt_pk_bf16(a[2], a[3]); w.z = cvt_pk_bf16(b[0], b[1]); w.w = cvt_pk_bf16(b[2], b[3]); return w; }
; #define GAS __attribute__((address_space(1)))
;     __device__ __forceinline__ void operator()(const f32x4 (&acc)[2][2][4][2], const Unit& u, int wr, int wc, int fr_, int fq_) const {
;     ...
;                 for (int m = 0; m < 4; ++m) { const int row = row0 + ai * HALF + m * 16;
;                     float sc = 1.f; if constexpr (MODE == EP_Q || MODE == EP_KV) sc = ((const GAS float*)rs)[row]; if constexpr (MODE == EP_GATE) { if (u.pn < 12) sc = ((const GAS float*)rs2)[row]; }
;                     if constexpr (MODE == EP_G2) { if (kind == 0) sc = ((const GAS float*)rs)[row]; else if (kind == 1) sc = ((const GAS float*)rs2)[row]; }
; #pragma unroll
;                     for (int bj = 0; bj < 2; ++bj) { const int col = colt + bj * HALF; f32x4 v0 = acc[ai][bj][m][0] * sc, v1 = acc[ai][bj][m][1] * sc;
;                         if constexpr (MODE == EP_STORE) { *(GAS u32x4*)(O + (size_t)row * ldc + col) = pack8(v0, v1); }
;                         else if constexpr (MODE == EP_BR) {
;                             ((GAS u32x4*)O)[((size_t)((((pm * 12 + u.pn) * 2 + ai) * 4 + m) * 2 + bj)) * 512 + wv_ * 64 + ln_] = pack8(v0, v1); }
;                         else if constexpr (MODE == EP_Q) { *(GAS u32x4*)(O + (size_t)row * ldc + col) = pack8(v0, v1); }
;                         else if constexpr (MODE == EP_G2) {
;                             if (kind == 0) *(GAS u32x4*)(O + (size_t)row * QW + col) = pack8(v0, v1);
;                             else if (kind == 1) { if (col < 512) *(GAS u32x4*)(O2 + (size_t)row * QW + (col >> 6) * QKD + (col & 63)) = pack8(v0, v1); else *(GAS u32x4*)(O3 + (size_t)row * VW + (col - 512)) = pack8(v0, v1); }
;                             else *(GAS u32x4*)(O4 + (size_t)row * 512 + col) = pack8(v0, v1); }
.LBB0_583:
	s_and_b64 s[60:61], exec, s[58:59]
	s_cselect_b32 s37, s84, s86
	s_cselect_b32 s53, s83, s85
	v_mov_b32_e32 v130, s53
	v_mov_b32_e32 v131, s37
	v_lshl_add_u64 v[130:131], v[156:157], 2, v[130:131]
	s_nop 1
	v_mov_b32_e32 v164, v198
.LBB0_584:
	s_nop 0
	v_or_b32_e32 v130, 48, v156
	v_ashrrev_i32_e32 v131, 31, v130
	v_mad_i64_i32 v[158:159], s[60:61], v130, s95, 0
	v_lshlrev_b64 v[160:161], 10, v[130:131]
	v_pk_mul_f32 v[168:169], v[70:71], v[164:165] op_sel_hi:[1,0]
	v_pk_mul_f32 v[172:173], v[68:69], v[164:165] op_sel_hi:[1,0]
	v_pk_mul_f32 v[166:167], v[66:67], v[164:165] op_sel_hi:[1,0]
	v_pk_mul_f32 v[170:171], v[64:65], v[164:165] op_sel_hi:[1,0]
	s_and_b64 vcc, exec, s[46:47]
	s_mov_b64 s[60:61], -1
	s_cbranch_vccnz .LBB0_594
	s_and_b64 vcc, exec, s[44:45]
	s_cbranch_vccnz .LBB0_587
	v_lshl_add_u64 v[162:163], s[28:29], 0, v[160:161]
	v_lshl_add_u64 v[192:193], v[154:155], 1, v[162:163]
	s_mov_b64 s[60:61], 0
	v_cvt_pk_bf16_f32 v130, v172, v173
	v_cvt_pk_bf16_f32 v131, v168, v169
	v_cvt_pk_bf16_f32 v132, v170, v171
	v_cvt_pk_bf16_f32 v133, v166, v167

; #define GAS __attribute__((address_space(1)))
; __device__ __forceinline__ u32x4 pack8(const f32x4& a, const f32x4& b) { u32x4 w; w.x = cvt_pk_bf16(a[0], a[1]); w.y = cvt_pk_bf16(a[2], a[3]); w.z = cvt_pk_bf16(b[0], b[1]); w.w = cvt_pk_bf16(b[2], b[3]); return w; }
; #define GAS __attribute__((address_space(1)))
;     __device__ __forceinline__ void operator()(const f32x4 (&acc)[2][2][4][2], const Unit& u, int wr, int wc, int fr_, int fq_) const {
;     ...
;                 for (int m = 0; m < 4; ++m) { const int row = row0 + ai * HALF + m * 16;
;                     float sc = 1.f; if constexpr (MODE == EP_Q || MODE == EP_KV) sc = ((const GAS float*)rs)[row]; if constexpr (MODE == EP_GATE) { if (u.pn < 12) sc = ((const GAS float*)rs2)[row]; }
;                     if constexpr (MODE == EP_G2) { if (kind == 0) sc = ((const GAS float*)rs)[row]; else if (kind == 1) sc = ((const GAS float*)rs2)[row]; }
; #pragma unroll
;                     for (int bj = 0; bj < 2; ++bj) { const int col = colt + bj * HALF; f32x4 v0 = acc[ai][bj][m][0] * sc, v1 = acc[ai][bj][m][1] * sc;
;                         if constexpr (MODE == EP_STORE) { *(GAS u32x4*)(O + (size_t)row * ldc + col) = pack8(v0, v1); }
;                         else if constexpr (MODE == EP_BR) {
;                             ((GAS u32x4*)O)[((size_t)((((pm * 12 + u.pn) * 2 + ai) * 4 + m) * 2 + bj)) * 512 + wv_ * 64 + ln_] = pack8(v0, v1); }
;                         else if constexpr (MODE == EP_Q) { *(GAS u32x4*)(O + (size_t)row * ldc + col) = pack8(v0, v1); }
;                         else if constexpr (MODE == EP_G2) {
;                             if (kind == 0) *(GAS u32x4*)(O + (size_t)row * QW + col) = pack8(v0, v1);
;                             else if (kind == 1) { if (col < 512) *(GAS u32x4*)(O2 + (size_t)row * QW + (col >> 6) * QKD + (col & 63)) = pack8(v0, v1); else *(GAS u32x4*)(O3 + (size_t)row * VW + (col - 512)) = pack8(v0, v1); }
;                             else *(GAS u32x4*)(O4 + (size_t)row * 512 + col) = pack8(v0, v1); }
.LBB0_607:
	s_and_b64 s[60:61], exec, s[58:59]
	s_cselect_b32 s37, s84, s86
	s_cselect_b32 s53, s83, s85
	v_mov_b32_e32 v130, s53
	v_mov_b32_e32 v131, s37
	v_lshl_add_u64 v[130:131], v[156:157], 2, v[130:131]
	s_nop 1
	v_mov_b32_e32 v164, v199
.LBB0_608:
	s_nop 0
	v_add_u32_e32 v130, 0x80, v156
	v_ashrrev_i32_e32 v131, 31, v130
	v_mad_i64_i32 v[158:159], s[60:61], v130, s95, 0
	v_lshlrev_b64 v[160:161], 10, v[130:131]
	v_pk_mul_f32 v[168:169], v[30:31], v[164:165] op_sel_hi:[1,0]
	v_pk_mul_f32 v[172:173], v[28:29], v[164:165] op_sel_hi:[1,0]
	v_pk_mul_f32 v[166:167], v[26:27], v[164:165] op_sel_hi:[1,0]
	v_pk_mul_f32 v[170:171], v[24:25], v[164:165] op_sel_hi:[1,0]
	s_and_b64 vcc, exec, s[46:47]
	s_mov_b64 s[60:61], -1
	s_cbranch_vccnz .LBB0_618
	s_and_b64 vcc, exec, s[44:45]
	s_cbranch_vccnz .LBB0_611
	v_lshl_add_u64 v[162:163], s[28:29], 0, v[160:161]
	v_lshl_add_u64 v[192:193], v[154:155], 1, v[162:163]
	s_mov_b64 s[60:61], 0
	v_cvt_pk_bf16_f32 v130, v172, v173
	v_cvt_pk_bf16_f32 v131, v168, v169
	v_cvt_pk_bf16_f32 v132, v170, v171
	v_cvt_pk_bf16_f32 v133, v166, v167

; #define GAS __attribute__((address_space(1)))
; __device__ __forceinline__ u32x4 pack8(const f32x4& a, const f32x4& b) { u32x4 w; w.x = cvt_pk_bf16(a[0], a[1]); w.y = cvt_pk_bf16(a[2], a[3]); w.z = cvt_pk_bf16(b[0], b[1]); w.w = cvt_pk_bf16(b[2], b[3]); return w; }
; #define GAS __attribute__((address_space(1)))
;     __device__ __forceinline__ void operator()(const f32x4 (&acc)[2][2][4][2], const Unit& u, int wr, int wc, int fr_, int fq_) const {
;     ...
;                 for (int m = 0; m < 4; ++m) { const int row = row0 + ai * HALF + m * 16;
;                     float sc = 1.f; if constexpr (MODE == EP_Q || MODE == EP_KV) sc = ((const GAS float*)rs)[row]; if constexpr (MODE == EP_GATE) { if (u.pn < 12) sc = ((const GAS float*)rs2)[row]; }
;                     if constexpr (MODE == EP_G2) { if (kind == 0) sc = ((const GAS float*)rs)[row]; else if (kind == 1) sc = ((const GAS float*)rs2)[row]; }
; #pragma unroll
;                     for (int bj = 0; bj < 2; ++bj) { const int col = colt + bj * HALF; f32x4 v0 = acc[ai][bj][m][0] * sc, v1 = acc[ai][bj][m][1] * sc;
;                         if constexpr (MODE == EP_STORE) { *(GAS u32x4*)(O + (size_t)row * ldc + col) = pack8(v0, v1); }
;                         else if constexpr (MODE == EP_BR) {
;                             ((GAS u32x4*)O)[((size_t)((((pm * 12 + u.pn) * 2 + ai) * 4 + m) * 2 + bj)) * 512 + wv_ * 64 + ln_] = pack8(v0, v1); }
;                         else if constexpr (MODE == EP_Q) { *(GAS u32x4*)(O + (size_t)row * ldc + col) = pack8(v0, v1); }
;                         else if constexpr (MODE == EP_G2) {
;                             if (kind == 0) *(GAS u32x4*)(O + (size_t)row * QW + col) = pack8(v0, v1);
;                             else if (kind == 1) { if (col < 512) *(GAS u32x4*)(O2 + (size_t)row * QW + (col >> 6) * QKD + (col & 63)) = pack8(v0, v1); else *(GAS u32x4*)(O3 + (size_t)row * VW + (col - 512)) = pack8(v0, v1); }
;                             else *(GAS u32x4*)(O4 + (size_t)row * 512 + col) = pack8(v0, v1); }
.LBB0_631:
	s_and_b64 s[60:61], exec, s[58:59]
	s_cselect_b32 s37, s84, s86
	s_cselect_b32 s53, s83, s85
	v_mov_b32_e32 v130, s53
	v_mov_b32_e32 v131, s37
	v_lshl_add_u64 v[130:131], v[156:157], 2, v[130:131]
	s_nop 1
	v_mov_b32_e32 v164, v200
.LBB0_632:
	s_nop 0
	v_add_u32_e32 v130, 0x90, v156
	v_ashrrev_i32_e32 v131, 31, v130
	v_mad_i64_i32 v[158:159], s[60:61], v130, s95, 0
	v_lshlrev_b64 v[160:161], 10, v[130:131]
	v_pk_mul_f32 v[168:169], v[22:23], v[164:165] op_sel_hi:[1,0]
	v_pk_mul_f32 v[172:173], v[20:21], v[164:165] op_sel_hi:[1,0]
	v_pk_mul_f32 v[166:167], v[18:19], v[164:165] op_sel_hi:[1,0]
	v_pk_mul_f32 v[170:171], v[16:17], v[164:165] op_sel_hi:[1,0]
	s_and_b64 vcc, exec, s[46:47]
	s_mov_b64 s[60:61], -1
	s_cbranch_vccnz .LBB0_642
	s_and_b64 vcc, exec, s[44:45]
	s_cbranch_vccnz .LBB0_635
	v_lshl_add_u64 v[162:163], s[28:29], 0, v[160:161]
	v_lshl_add_u64 v[192:193], v[154:155], 1, v[162:163]
	s_mov_b64 s[60:61], 0
	v_cvt_pk_bf16_f32 v130, v172, v173
	v_cvt_pk_bf16_f32 v131, v168, v169
	v_cvt_pk_bf16_f32 v132, v170, v171
	v_cvt_pk_bf16_f32 v133, v166, v167

; #define GAS __attribute__((address_space(1)))
; __device__ __forceinline__ u32x4 pack8(const f32x4& a, const f32x4& b) { u32x4 w; w.x = cvt_pk_bf16(a[0], a[1]); w.y = cvt_pk_bf16(a[2], a[3]); w.z = cvt_pk_bf16(b[0], b[1]); w.w = cvt_pk_bf16(b[2], b[3]); return w; }
; #define GAS __attribute__((address_space(1)))
;     __device__ __forceinline__ void operator()(const f32x4 (&acc)[2][2][4][2], const Unit& u, int wr, int wc, int fr_, int fq_) const {
;     ...
;                 for (int m = 0; m < 4; ++m) { const int row = row0 + ai * HALF + m * 16;
;                     float sc = 1.f; if constexpr (MODE == EP_Q || MODE == EP_KV) sc = ((const GAS float*)rs)[row]; if constexpr (MODE == EP_GATE) { if (u.pn < 12) sc = ((const GAS float*)rs2)[row]; }
;                     if constexpr (MODE == EP_G2) { if (kind == 0) sc = ((const GAS float*)rs)[row]; else if (kind == 1) sc = ((const GAS float*)rs2)[row]; }
; #pragma unroll
;                     for (int bj = 0; bj < 2; ++bj) { const int col = colt + bj * HALF; f32x4 v0 = acc[ai][bj][m][0] * sc, v1 = acc[ai][bj][m][1] * sc;
;                         if constexpr (MODE == EP_STORE) { *(GAS u32x4*)(O + (size_t)row * ldc + col) = pack8(v0, v1); }
;                         else if constexpr (MODE == EP_BR) {
;                             ((GAS u32x4*)O)[((size_t)((((pm * 12 + u.pn) * 2 + ai) * 4 + m) * 2 + bj)) * 512 + wv_ * 64 + ln_] = pack8(v0, v1); }
;                         else if constexpr (MODE == EP_Q) { *(GAS u32x4*)(O + (size_t)row * ldc + col) = pack8(v0, v1); }
;                         else if constexpr (MODE == EP_G2) {
;                             if (kind == 0) *(GAS u32x4*)(O + (size_t)row * QW + col) = pack8(v0, v1);
;                             else if (kind == 1) { if (col < 512) *(GAS u32x4*)(O2 + (size_t)row * QW + (col >> 6) * QKD + (col & 63)) = pack8(v0, v1); else *(GAS u32x4*)(O3 + (size_t)row * VW + (col - 512)) = pack8(v0, v1); }
;                             else *(GAS u32x4*)(O4 + (size_t)row * 512 + col) = pack8(v0, v1); }
.LBB0_655:
	s_and_b64 s[60:61], exec, s[58:59]
	s_cselect_b32 s37, s84, s86
	s_cselect_b32 s53, s83, s85
	v_mov_b32_e32 v130, s53
	v_mov_b32_e32 v131, s37
	v_lshl_add_u64 v[130:131], v[156:157], 2, v[130:131]
	s_nop 1
	v_mov_b32_e32 v164, v201
.LBB0_656:
	s_nop 0
	v_add_u32_e32 v130, 0xa0, v156
	v_ashrrev_i32_e32 v131, 31, v130
	v_mad_i64_i32 v[158:159], s[60:61], v130, s95, 0
	v_lshlrev_b64 v[160:161], 10, v[130:131]
	v_pk_mul_f32 v[168:169], v[14:15], v[164:165] op_sel_hi:[1,0]
	v_pk_mul_f32 v[172:173], v[12:13], v[164:165] op_sel_hi:[1,0]
	v_pk_mul_f32 v[166:167], v[10:11], v[164:165] op_sel_hi:[1,0]
	v_pk_mul_f32 v[170:171], v[8:9], v[164:165] op_sel_hi:[1,0]
	s_and_b64 vcc, exec, s[46:47]
	s_mov_b64 s[60:61], -1
	s_cbranch_vccnz .LBB0_666
	s_and_b64 vcc, exec, s[44:45]
	s_cbranch_vccnz .LBB0_659
	v_lshl_add_u64 v[162:163], s[28:29], 0, v[160:161]
	v_lshl_add_u64 v[192:193], v[154:155], 1, v[162:163]
	s_mov_b64 s[60:61], 0
	v_cvt_pk_bf16_f32 v130, v172, v173
	v_cvt_pk_bf16_f32 v131, v168, v169
	v_cvt_pk_bf16_f32 v132, v170, v171
	v_cvt_pk_bf16_f32 v133, v166, v167

; #define GAS __attribute__((address_space(1)))
; __device__ __forceinline__ u32x4 pack8(const f32x4& a, const f32x4& b) { u32x4 w; w.x = cvt_pk_bf16(a[0], a[1]); w.y = cvt_pk_bf16(a[2], a[3]); w.z = cvt_pk_bf16(b[0], b[1]); w.w = cvt_pk_bf16(b[2], b[3]); return w; }
; #define GAS __attribute__((address_space(1)))
;     __device__ __forceinline__ void operator()(const f32x4 (&acc)[2][2][4][2], const Unit& u, int wr, int wc, int fr_, int fq_) const {
;     ...
;                 for (int m = 0; m < 4; ++m) { const int row = row0 + ai * HALF + m * 16;
;                     float sc = 1.f; if constexpr (MODE == EP_Q || MODE == EP_KV) sc = ((const GAS float*)rs)[row]; if constexpr (MODE == EP_GATE) { if (u.pn < 12) sc = ((const GAS float*)rs2)[row]; }
;                     if constexpr (MODE == EP_G2) { if (kind == 0) sc = ((const GAS float*)rs)[row]; else if (kind == 1) sc = ((const GAS float*)rs2)[row]; }
; #pragma unroll
;                     for (int bj = 0; bj < 2; ++bj) { const int col = colt + bj * HALF; f32x4 v0 = acc[ai][bj][m][0] * sc, v1 = acc[ai][bj][m][1] * sc;
;                         if constexpr (MODE == EP_STORE) { *(GAS u32x4*)(O + (size_t)row * ldc + col) = pack8(v0, v1); }
;                         else if constexpr (MODE == EP_BR) {
;                             ((GAS u32x4*)O)[((size_t)((((pm * 12 + u.pn) * 2 + ai) * 4 + m) * 2 + bj)) * 512 + wv_ * 64 + ln_] = pack8(v0, v1); }
;                         else if constexpr (MODE == EP_Q) { *(GAS u32x4*)(O + (size_t)row * ldc + col) = pack8(v0, v1); }
;                         else if constexpr (MODE == EP_G2) {
;                             if (kind == 0) *(GAS u32x4*)(O + (size_t)row * QW + col) = pack8(v0, v1);
;                             else if (kind == 1) { if (col < 512) *(GAS u32x4*)(O2 + (size_t)row * QW + (col >> 6) * QKD + (col & 63)) = pack8(v0, v1); else *(GAS u32x4*)(O3 + (size_t)row * VW + (col - 512)) = pack8(v0, v1); }
;                             else *(GAS u32x4*)(O4 + (size_t)row * 512 + col) = pack8(v0, v1); }
.LBB0_679:
	s_and_b64 s[42:43], exec, s[58:59]
	s_cselect_b32 s37, s84, s86
	s_cselect_b32 s42, s83, s85
	v_mov_b32_e32 v130, s42
	v_mov_b32_e32 v131, s37
	v_lshl_add_u64 v[130:131], v[156:157], 2, v[130:131]
	s_nop 1
	v_mov_b32_e32 v162, v202
.LBB0_680:
	s_nop 0
	v_add_u32_e32 v130, 0xb0, v156
	v_ashrrev_i32_e32 v131, 31, v130
	v_mad_i64_i32 v[156:157], s[42:43], v130, s95, 0
	v_lshlrev_b64 v[158:159], 10, v[130:131]
	v_pk_mul_f32 v[166:167], v[6:7], v[162:163] op_sel_hi:[1,0]
	v_pk_mul_f32 v[170:171], v[4:5], v[162:163] op_sel_hi:[1,0]
	v_pk_mul_f32 v[164:165], v[2:3], v[162:163] op_sel_hi:[1,0]
	v_pk_mul_f32 v[168:169], v[0:1], v[162:163] op_sel_hi:[1,0]
	s_and_b64 vcc, exec, s[46:47]
	s_mov_b64 s[42:43], -1
	s_cbranch_vccnz .LBB0_690
	s_and_b64 vcc, exec, s[44:45]
	s_cbranch_vccnz .LBB0_683
	v_lshl_add_u64 v[160:161], s[28:29], 0, v[158:159]
	v_lshl_add_u64 v[172:173], v[154:155], 1, v[160:161]
	s_mov_b64 s[42:43], 0
	v_cvt_pk_bf16_f32 v130, v170, v171
	v_cvt_pk_bf16_f32 v131, v166, v167
	v_cvt_pk_bf16_f32 v132, v168, v169
	v_cvt_pk_bf16_f32 v133, v164, v165

; #define GAS __attribute__((address_space(1)))
;     __device__ __forceinline__ void operator()(const f32x4 (&acc)[2][2][4][2], const Unit& u, int wr, int wc, int fr_, int fq_) const {
;     ...
;                 for (int m = 0; m < 4; ++m) { const int row = row0 + ai * HALF + m * 16;
;                     float sc = 1.f; if constexpr (MODE == EP_Q || MODE == EP_KV) sc = ((const GAS float*)rs)[row]; if constexpr (MODE == EP_GATE) { if (u.pn < 12) sc = ((const GAS float*)rs2)[row]; }
;                     if constexpr (MODE == EP_G2) { if (kind == 0) sc = ((const GAS float*)rs)[row]; else if (kind == 1) sc = ((const GAS float*)rs2)[row]; }
; #pragma unroll
;                     for (int bj = 0; bj < 2; ++bj) { const int col = colt + bj * HALF; f32x4 v0 = acc[ai][bj][m][0] * sc, v1 = acc[ai][bj][m][1] * sc;
;                         if constexpr (MODE == EP_STORE) { *(GAS u32x4*)(O + (size_t)row * ldc + col) = pack8(v0, v1); }
;                         else if constexpr (MODE == EP_BR) {
;                             ((GAS u32x4*)O)[((size_t)((((pm * 12 + u.pn) * 2 + ai) * 4 + m) * 2 + bj)) * 512 + wv_ * 64 + ln_] = pack8(v0, v1); }
;                         else if constexpr (MODE == EP_Q) { *(GAS u32x4*)(O + (size_t)row * ldc + col) = pack8(v0, v1); }
;                         else if constexpr (MODE == EP_G2) {
;                             if (kind == 0) *(GAS u32x4*)(O + (size_t)row * QW + col) = pack8(v0, v1);
;                             else if (kind == 1) { if (col < 512) *(GAS u32x4*)(O2 + (size_t)row * QW + (col >> 6) * QKD + (col & 63)) = pack8(v0, v1); else *(GAS u32x4*)(O3 + (size_t)row * VW + (col - 512)) = pack8(v0, v1); }
;                             else *(GAS u32x4*)(O4 + (size_t)row * 512 + col) = pack8(v0, v1); }
;                         else if constexpr (MODE == EP_KV) {
;                             if (col < 512) *(GAS u32x4*)(O + (size_t)row * QW + (col >> 6) * QKD + (col & 63)) = pack8(v0, v1);
;                             else *(GAS u32x4*)(O2 + (size_t)row * VW + (col - 512)) = pack8(v0, v1); }
;                         else if constexpr (MODE == EP_GATE) {
;                             GAS u32x4* brs = (GAS u32x4*)O2 + ((size_t)((ai * 4 + m) * 2 + bj)) * 512 + wv_ * 64 + ln_;
;                             if (u.pn >= 12) { *brs = pack8(v0, v1); continue; }
;                             const int n = u.pn >> 2, d = col - n * 1024;
.LBB0_936:
	v_mov_b32_e32 v135, v175
	s_lshl_b32 s16, s44, 8
	v_mbcnt_lo_u32_b32 v135, -1, v135
	v_readlane_b32 s17, v255, 56
	v_mbcnt_hi_u32_b32 v144, -1, v135
	s_add_i32 s16, s16, s17
	v_and_or_b32 v146, v144, 15, s16
	v_readlane_b32 s16, v255, 54
	s_cmp_lt_i32 s46, 12
	v_ashrrev_i32_e32 v147, 31, v146
	v_readlane_b32 s17, v255, 55
	s_cselect_b64 s[86:87], -1, 0
	s_cmp_gt_i32 s46, 11
	v_mov_b32_e32 v150, 1.0
	v_lshl_add_u64 v[148:149], v[146:147], 2, s[16:17]
	s_cbranch_scc1 .LBB0_938
	global_load_dword v150, v[148:149], off
	global_load_dword v196, v[148:149], off offset:64
	global_load_dword v197, v[148:149], off offset:128
	global_load_dword v198, v[148:149], off offset:192
	global_load_dword v199, v[148:149], off offset:512
	global_load_dword v200, v[148:149], off offset:576
	global_load_dword v201, v[148:149], off offset:640
	global_load_dword v202, v[148:149], off offset:704
	s_waitcnt vmcnt(0)
.LBB0_938:
	s_lshl_b32 s16, s46, 8
	v_readlane_b32 s17, v255, 57
	s_or_b32 s16, s16, s17
	v_ashrrev_i32_e32 v135, 1, v144
	s_cmp_lt_i32 s46, 12
	v_and_b32_e32 v135, -8, v135
	s_cselect_b64 s[76:77], -1, 0
	s_lshl_b32 s20, s46, 4
	v_add_u32_e32 v142, s16, v135
	s_ashr_i32 s16, s46, 2
	s_lshl_b32 s17, s44, 6
	s_and_b32 s20, s20, 48
	s_lshl_b32 s37, s16, 10
	s_or_b32 s84, s20, s17
	s_cmp_gt_i32 s16, 0
	s_cselect_b64 s[42:43], -1, 0
	s_cmp_gt_i32 s16, 1
	v_readlane_b32 s16, v255, 60
	v_ashrrev_i32_e32 v145, 31, v144
	v_readlane_b32 s17, v255, 61
	v_cndmask_b32_e64 v135, 0, 1, s[42:43]
	s_cselect_b64 s[82:83], -1, 0
	v_pk_mul_f32 v[128:129], v[128:129], v[150:151] op_sel_hi:[1,0]
	v_pk_mul_f32 v[152:153], v[126:127], v[150:151] op_sel_hi:[1,0]
	v_pk_mul_f32 v[124:125], v[124:125], v[150:151] op_sel_hi:[1,0]
	v_pk_mul_f32 v[126:127], v[122:123], v[150:151] op_sel_hi:[1,0]
	v_lshl_add_u64 v[122:123], v[144:145], 4, s[16:17]
	s_mov_b64 s[44:45], -1
	s_and_b64 vcc, exec, s[76:77]
	v_ashrrev_i32_e32 v143, 31, v142
	v_cmp_ne_u32_e64 s[42:43], 1, v135
	s_cbranch_vccz .LBB0_946
	v_lshl_add_u64 v[154:155], v[142:143], 2, s[56:57]
	global_load_dwordx4 v[158:161], v[154:155], off offset:16
	s_nop 0
	global_load_dwordx4 v[154:157], v[154:155], off
	s_nop 0
	global_load_dwordx4 v[168:171], v[122:123], off
	s_ashr_i32 s85, s84, 31
	s_lshl_b64 s[44:45], s[84:85], 13
	s_add_u32 s44, s5, s44
	s_addc_u32 s45, s60, s45
	s_and_b64 vcc, exec, s[42:43]
	s_waitcnt vmcnt(1)
	v_add_f32_e32 v135, v152, v154
	v_mul_f32_e32 v135, 0xbfb8aa3b, v135
	v_exp_f32_e32 v135, v135
	s_waitcnt vmcnt(0)
	v_lshlrev_b32_e32 v162, 16, v168
	v_and_b32_e32 v163, 0xffff0000, v168
	v_add_f32_e32 v135, 1.0, v135
	v_rcp_f32_e32 v154, v135
	v_add_f32_e32 v135, v153, v155
	v_mul_f32_e32 v135, 0xbfb8aa3b, v135
	v_exp_f32_e32 v135, v135
	s_nop 0
	v_add_f32_e32 v135, 1.0, v135
	v_rcp_f32_e32 v155, v135
	v_add_f32_e32 v135, v128, v156
	v_mul_f32_e32 v135, 0xbfb8aa3b, v135
	v_exp_f32_e32 v135, v135
	v_pk_mul_f32 v[154:155], v[154:155], v[162:163]
	v_lshlrev_b32_e32 v162, 16, v169
	v_and_b32_e32 v163, 0xffff0000, v169
	v_add_f32_e32 v135, 1.0, v135
	v_rcp_f32_e32 v156, v135
	v_add_f32_e32 v135, v129, v157
	v_mul_f32_e32 v135, 0xbfb8aa3b, v135
	v_exp_f32_e32 v135, v135
	s_nop 0
	v_add_f32_e32 v135, 1.0, v135
	v_rcp_f32_e32 v157, v135
	v_add_f32_e32 v135, v126, v158
	v_mul_f32_e32 v135, 0xbfb8aa3b, v135
	v_exp_f32_e32 v135, v135
	v_pk_mul_f32 v[156:157], v[156:157], v[162:163]
	v_lshlrev_b32_e32 v162, 16, v170
	v_and_b32_e32 v163, 0xffff0000, v170
	v_add_f32_e32 v135, 1.0, v135
	v_rcp_f32_e32 v158, v135
	v_add_f32_e32 v135, v127, v159
	v_mul_f32_e32 v135, 0xbfb8aa3b, v135
	v_exp_f32_e32 v135, v135
	s_nop 0
	v_add_f32_e32 v135, 1.0, v135
	v_rcp_f32_e32 v159, v135
	v_add_f32_e32 v135, v124, v160
	v_mul_f32_e32 v135, 0xbfb8aa3b, v135
	v_exp_f32_e32 v135, v135
	v_pk_mul_f32 v[158:159], v[158:159], v[162:163]
	v_lshlrev_b32_e32 v162, 16, v171
	v_and_b32_e32 v163, 0xffff0000, v171
	v_add_f32_e32 v135, 1.0, v135
	v_rcp_f32_e32 v160, v135
	v_add_f32_e32 v135, v125, v161
	v_mul_f32_e32 v135, 0xbfb8aa3b, v135
	v_exp_f32_e32 v135, v135
	s_nop 0
	v_add_f32_e32 v135, 1.0, v135
	v_rcp_f32_e32 v161, v135
	s_nop 0
	v_pk_mul_f32 v[160:161], v[160:161], v[162:163]
	v_lshl_add_u64 v[162:163], v[144:145], 4, s[44:45]
	s_cbranch_vccnz .LBB0_941
	global_load_dwordx4 v[168:171], v[162:163], off
	s_waitcnt vmcnt(0)
	v_lshlrev_b32_e32 v172, 16, v168
	v_and_b32_e32 v173, 0xffff0000, v168
	v_lshlrev_b32_e32 v168, 16, v169
	v_and_b32_e32 v169, 0xffff0000, v169
	v_pk_add_f32 v[156:157], v[156:157], v[168:169]
	v_lshlrev_b32_e32 v168, 16, v170
	v_and_b32_e32 v169, 0xffff0000, v170
	v_pk_add_f32 v[158:159], v[158:159], v[168:169]
	v_lshlrev_b32_e32 v168, 16, v171
	v_and_b32_e32 v169, 0xffff0000, v171
	v_pk_add_f32 v[154:155], v[154:155], v[172:173]
	v_pk_add_f32 v[160:161], v[160:161], v[168:169]

; #define GAS __attribute__((address_space(1)))
;     __device__ __forceinline__ void operator()(const f32x4 (&acc)[2][2][4][2], const Unit& u, int wr, int wc, int fr_, int fq_) const {
;     ...
;                 for (int m = 0; m < 4; ++m) { const int row = row0 + ai * HALF + m * 16;
;                     float sc = 1.f; if constexpr (MODE == EP_Q || MODE == EP_KV) sc = ((const GAS float*)rs)[row]; if constexpr (MODE == EP_GATE) { if (u.pn < 12) sc = ((const GAS float*)rs2)[row]; }
;                     if constexpr (MODE == EP_G2) { if (kind == 0) sc = ((const GAS float*)rs)[row]; else if (kind == 1) sc = ((const GAS float*)rs2)[row]; }
; #pragma unroll
;                     for (int bj = 0; bj < 2; ++bj) { const int col = colt + bj * HALF; f32x4 v0 = acc[ai][bj][m][0] * sc, v1 = acc[ai][bj][m][1] * sc;
;                         if constexpr (MODE == EP_STORE) { *(GAS u32x4*)(O + (size_t)row * ldc + col) = pack8(v0, v1); }
;                         else if constexpr (MODE == EP_BR) {
;                             ((GAS u32x4*)O)[((size_t)((((pm * 12 + u.pn) * 2 + ai) * 4 + m) * 2 + bj)) * 512 + wv_ * 64 + ln_] = pack8(v0, v1); }
;                         else if constexpr (MODE == EP_Q) { *(GAS u32x4*)(O + (size_t)row * ldc + col) = pack8(v0, v1); }
;                         else if constexpr (MODE == EP_G2) {
;                             if (kind == 0) *(GAS u32x4*)(O + (size_t)row * QW + col) = pack8(v0, v1);
;                             else if (kind == 1) { if (col < 512) *(GAS u32x4*)(O2 + (size_t)row * QW + (col >> 6) * QKD + (col & 63)) = pack8(v0, v1); else *(GAS u32x4*)(O3 + (size_t)row * VW + (col - 512)) = pack8(v0, v1); }
;                             else *(GAS u32x4*)(O4 + (size_t)row * 512 + col) = pack8(v0, v1); }
;                         else if constexpr (MODE == EP_KV) {
;                             if (col < 512) *(GAS u32x4*)(O + (size_t)row * QW + (col >> 6) * QKD + (col & 63)) = pack8(v0, v1);
;                             else *(GAS u32x4*)(O2 + (size_t)row * VW + (col - 512)) = pack8(v0, v1); }
;                         else if constexpr (MODE == EP_GATE) {
;                             GAS u32x4* brs = (GAS u32x4*)O2 + ((size_t)((ai * 4 + m) * 2 + bj)) * 512 + wv_ * 64 + ln_;
;                             if (u.pn >= 12) { *brs = pack8(v0, v1); continue; }
;                             const int n = u.pn >> 2, d = col - n * 1024;
.LBB0_958:
	v_cndmask_b32_e64 v114, 0, 1, s[86:87]
	v_cmp_ne_u32_e64 s[46:47], 1, v114
	s_andn2_b64 vcc, exec, s[86:87]
	v_mov_b32_e32 v116, 1.0
	s_cbranch_vccnz .LBB0_960
	s_nop 1
	v_mov_b32_e32 v116, v196
.LBB0_960:
	v_or_b32_e32 v114, 16, v146
	v_ashrrev_i32_e32 v115, 31, v114
	v_pk_mul_f32 v[110:111], v[110:111], v[116:117] op_sel_hi:[1,0]
	v_pk_mul_f32 v[118:119], v[108:109], v[116:117] op_sel_hi:[1,0]
	v_pk_mul_f32 v[106:107], v[106:107], v[116:117] op_sel_hi:[1,0]
	v_pk_mul_f32 v[108:109], v[104:105], v[116:117] op_sel_hi:[1,0]
	v_lshl_add_u64 v[104:105], v[144:145], 4, s[66:67]
	s_and_b64 vcc, exec, s[44:45]
	s_mov_b64 s[76:77], -1
	s_cbranch_vccnz .LBB0_968
	v_lshl_add_u64 v[120:121], v[142:143], 2, s[56:57]
	global_load_dwordx4 v[124:127], v[120:121], off offset:16
	s_nop 0
	global_load_dwordx4 v[120:123], v[120:121], off
	s_nop 0
	global_load_dwordx4 v[150:153], v[104:105], off
	s_or_b32 s76, s84, 2
	s_ashr_i32 s77, s76, 31
	s_lshl_b64 s[58:59], s[76:77], 13
	s_add_u32 s58, s5, s58
	s_addc_u32 s59, s60, s59
	s_and_b64 vcc, exec, s[42:43]
	s_waitcnt vmcnt(1)
	v_add_f32_e32 v117, v118, v120
	v_mul_f32_e32 v117, 0xbfb8aa3b, v117
	v_exp_f32_e32 v117, v117
	s_waitcnt vmcnt(0)
	v_lshlrev_b32_e32 v128, 16, v150
	v_and_b32_e32 v129, 0xffff0000, v150
	v_add_f32_e32 v117, 1.0, v117
	v_rcp_f32_e32 v120, v117
	v_add_f32_e32 v117, v119, v121
	v_mul_f32_e32 v117, 0xbfb8aa3b, v117
	v_exp_f32_e32 v117, v117
	s_nop 0
	v_add_f32_e32 v117, 1.0, v117
	v_rcp_f32_e32 v121, v117
	v_add_f32_e32 v117, v110, v122
	v_mul_f32_e32 v117, 0xbfb8aa3b, v117
	v_exp_f32_e32 v117, v117
	v_pk_mul_f32 v[120:121], v[120:121], v[128:129]
	v_lshlrev_b32_e32 v128, 16, v151
	v_and_b32_e32 v129, 0xffff0000, v151
	v_add_f32_e32 v117, 1.0, v117
	v_rcp_f32_e32 v122, v117
	v_add_f32_e32 v117, v111, v123
	v_mul_f32_e32 v117, 0xbfb8aa3b, v117
	v_exp_f32_e32 v117, v117
	s_nop 0
	v_add_f32_e32 v117, 1.0, v117
	v_rcp_f32_e32 v123, v117
	v_add_f32_e32 v117, v108, v124
	v_mul_f32_e32 v117, 0xbfb8aa3b, v117
	v_exp_f32_e32 v117, v117
	v_pk_mul_f32 v[122:123], v[122:123], v[128:129]
	v_lshlrev_b32_e32 v128, 16, v152
	v_and_b32_e32 v129, 0xffff0000, v152
	v_add_f32_e32 v117, 1.0, v117
	v_rcp_f32_e32 v124, v117
	v_add_f32_e32 v117, v109, v125
	v_mul_f32_e32 v117, 0xbfb8aa3b, v117
	v_exp_f32_e32 v117, v117
	s_nop 0
	v_add_f32_e32 v117, 1.0, v117
	v_rcp_f32_e32 v125, v117
	v_add_f32_e32 v117, v106, v126
	v_mul_f32_e32 v117, 0xbfb8aa3b, v117
	v_exp_f32_e32 v117, v117
	v_pk_mul_f32 v[124:125], v[124:125], v[128:129]
	v_lshlrev_b32_e32 v128, 16, v153
	v_and_b32_e32 v129, 0xffff0000, v153
	v_add_f32_e32 v117, 1.0, v117
	v_rcp_f32_e32 v126, v117
	v_add_f32_e32 v117, v107, v127
	v_mul_f32_e32 v117, 0xbfb8aa3b, v117
	v_exp_f32_e32 v117, v117
	s_nop 0
	v_add_f32_e32 v117, 1.0, v117
	v_rcp_f32_e32 v127, v117
	s_nop 0
	v_pk_mul_f32 v[126:127], v[126:127], v[128:129]
	v_lshl_add_u64 v[128:129], v[144:145], 4, s[58:59]
	s_cbranch_vccnz .LBB0_963
	global_load_dwordx4 v[150:153], v[128:129], off
	s_waitcnt vmcnt(0)
	v_lshlrev_b32_e32 v154, 16, v150
	v_and_b32_e32 v155, 0xffff0000, v150
	v_lshlrev_b32_e32 v150, 16, v151
	v_and_b32_e32 v151, 0xffff0000, v151
	v_pk_add_f32 v[122:123], v[122:123], v[150:151]
	v_lshlrev_b32_e32 v150, 16, v152
	v_and_b32_e32 v151, 0xffff0000, v152
	v_pk_add_f32 v[124:125], v[124:125], v[150:151]
	v_lshlrev_b32_e32 v150, 16, v153
	v_and_b32_e32 v151, 0xffff0000, v153
	v_pk_add_f32 v[120:121], v[120:121], v[154:155]
	v_pk_add_f32 v[126:127], v[126:127], v[150:151]

; #define GAS __attribute__((address_space(1)))
;     __device__ __forceinline__ void operator()(const f32x4 (&acc)[2][2][4][2], const Unit& u, int wr, int wc, int fr_, int fq_) const {
;     ...
;                 for (int m = 0; m < 4; ++m) { const int row = row0 + ai * HALF + m * 16;
;                     float sc = 1.f; if constexpr (MODE == EP_Q || MODE == EP_KV) sc = ((const GAS float*)rs)[row]; if constexpr (MODE == EP_GATE) { if (u.pn < 12) sc = ((const GAS float*)rs2)[row]; }
;                     if constexpr (MODE == EP_G2) { if (kind == 0) sc = ((const GAS float*)rs)[row]; else if (kind == 1) sc = ((const GAS float*)rs2)[row]; }
; #pragma unroll
;                     for (int bj = 0; bj < 2; ++bj) { const int col = colt + bj * HALF; f32x4 v0 = acc[ai][bj][m][0] * sc, v1 = acc[ai][bj][m][1] * sc;
;                         if constexpr (MODE == EP_STORE) { *(GAS u32x4*)(O + (size_t)row * ldc + col) = pack8(v0, v1); }
;                         else if constexpr (MODE == EP_BR) {
;                             ((GAS u32x4*)O)[((size_t)((((pm * 12 + u.pn) * 2 + ai) * 4 + m) * 2 + bj)) * 512 + wv_ * 64 + ln_] = pack8(v0, v1); }
;                         else if constexpr (MODE == EP_Q) { *(GAS u32x4*)(O + (size_t)row * ldc + col) = pack8(v0, v1); }
;                         else if constexpr (MODE == EP_G2) {
;                             if (kind == 0) *(GAS u32x4*)(O + (size_t)row * QW + col) = pack8(v0, v1);
;                             else if (kind == 1) { if (col < 512) *(GAS u32x4*)(O2 + (size_t)row * QW + (col >> 6) * QKD + (col & 63)) = pack8(v0, v1); else *(GAS u32x4*)(O3 + (size_t)row * VW + (col - 512)) = pack8(v0, v1); }
;                             else *(GAS u32x4*)(O4 + (size_t)row * 512 + col) = pack8(v0, v1); }
;                         else if constexpr (MODE == EP_KV) {
;                             if (col < 512) *(GAS u32x4*)(O + (size_t)row * QW + (col >> 6) * QKD + (col & 63)) = pack8(v0, v1);
;                             else *(GAS u32x4*)(O2 + (size_t)row * VW + (col - 512)) = pack8(v0, v1); }
;                         else if constexpr (MODE == EP_GATE) {
;                             GAS u32x4* brs = (GAS u32x4*)O2 + ((size_t)((ai * 4 + m) * 2 + bj)) * 512 + wv_ * 64 + ln_;
;                             if (u.pn >= 12) { *brs = pack8(v0, v1); continue; }
;                             const int n = u.pn >> 2, d = col - n * 1024;
.LBB0_979:
	s_nop 1
	v_mov_b32_e32 v98, v197
.LBB0_980:
	v_or_b32_e32 v96, 32, v146
	v_ashrrev_i32_e32 v97, 31, v96
	v_pk_mul_f32 v[94:95], v[94:95], v[98:99] op_sel_hi:[1,0]
	v_pk_mul_f32 v[100:101], v[92:93], v[98:99] op_sel_hi:[1,0]
	v_pk_mul_f32 v[90:91], v[90:91], v[98:99] op_sel_hi:[1,0]
	v_pk_mul_f32 v[92:93], v[88:89], v[98:99] op_sel_hi:[1,0]
	v_lshl_add_u64 v[88:89], v[144:145], 4, s[38:39]
	s_and_b64 vcc, exec, s[44:45]
	s_mov_b64 s[76:77], -1
	s_cbranch_vccnz .LBB0_988
	v_lshl_add_u64 v[102:103], v[142:143], 2, s[56:57]
	global_load_dwordx4 v[106:109], v[102:103], off offset:16
	s_nop 0
	global_load_dwordx4 v[102:105], v[102:103], off
	s_nop 0
	global_load_dwordx4 v[114:117], v[88:89], off
	s_or_b32 s76, s84, 4
	s_ashr_i32 s77, s76, 31
	s_lshl_b64 s[58:59], s[76:77], 13
	s_add_u32 s58, s5, s58
	s_addc_u32 s59, s60, s59
	s_and_b64 vcc, exec, s[42:43]
	s_waitcnt vmcnt(1)
	v_add_f32_e32 v99, v100, v102
	v_mul_f32_e32 v99, 0xbfb8aa3b, v99
	v_exp_f32_e32 v99, v99
	s_waitcnt vmcnt(0)
	v_lshlrev_b32_e32 v110, 16, v114
	v_and_b32_e32 v111, 0xffff0000, v114
	v_add_f32_e32 v99, 1.0, v99
	v_rcp_f32_e32 v102, v99
	v_add_f32_e32 v99, v101, v103
	v_mul_f32_e32 v99, 0xbfb8aa3b, v99
	v_exp_f32_e32 v99, v99
	s_nop 0
	v_add_f32_e32 v99, 1.0, v99
	v_rcp_f32_e32 v103, v99
	v_add_f32_e32 v99, v94, v104
	v_mul_f32_e32 v99, 0xbfb8aa3b, v99
	v_exp_f32_e32 v99, v99
	v_pk_mul_f32 v[102:103], v[102:103], v[110:111]
	v_lshlrev_b32_e32 v110, 16, v115
	v_and_b32_e32 v111, 0xffff0000, v115
	v_add_f32_e32 v99, 1.0, v99
	v_rcp_f32_e32 v104, v99
	v_add_f32_e32 v99, v95, v105
	v_mul_f32_e32 v99, 0xbfb8aa3b, v99
	v_exp_f32_e32 v99, v99
	s_nop 0
	v_add_f32_e32 v99, 1.0, v99
	v_rcp_f32_e32 v105, v99
	v_add_f32_e32 v99, v92, v106
	v_mul_f32_e32 v99, 0xbfb8aa3b, v99
	v_exp_f32_e32 v99, v99
	v_pk_mul_f32 v[104:105], v[104:105], v[110:111]
	v_lshlrev_b32_e32 v110, 16, v116
	v_and_b32_e32 v111, 0xffff0000, v116
	v_add_f32_e32 v99, 1.0, v99
	v_rcp_f32_e32 v106, v99
	v_add_f32_e32 v99, v93, v107
	v_mul_f32_e32 v99, 0xbfb8aa3b, v99
	v_exp_f32_e32 v99, v99
	s_nop 0
	v_add_f32_e32 v99, 1.0, v99
	v_rcp_f32_e32 v107, v99
	v_add_f32_e32 v99, v90, v108
	v_mul_f32_e32 v99, 0xbfb8aa3b, v99
	v_exp_f32_e32 v99, v99
	v_pk_mul_f32 v[106:107], v[106:107], v[110:111]
	v_lshlrev_b32_e32 v110, 16, v117
	v_and_b32_e32 v111, 0xffff0000, v117
	v_add_f32_e32 v99, 1.0, v99
	v_rcp_f32_e32 v108, v99
	v_add_f32_e32 v99, v91, v109
	v_mul_f32_e32 v99, 0xbfb8aa3b, v99
	v_exp_f32_e32 v99, v99
	s_nop 0
	v_add_f32_e32 v99, 1.0, v99
	v_rcp_f32_e32 v109, v99
	s_nop 0
	v_pk_mul_f32 v[108:109], v[108:109], v[110:111]
	v_lshl_add_u64 v[110:111], v[144:145], 4, s[58:59]
	s_cbranch_vccnz .LBB0_983
	global_load_dwordx4 v[114:117], v[110:111], off
	s_waitcnt vmcnt(0)
	v_lshlrev_b32_e32 v118, 16, v114
	v_and_b32_e32 v119, 0xffff0000, v114
	v_lshlrev_b32_e32 v114, 16, v115
	v_and_b32_e32 v115, 0xffff0000, v115
	v_pk_add_f32 v[104:105], v[104:105], v[114:115]
	v_lshlrev_b32_e32 v114, 16, v116
	v_and_b32_e32 v115, 0xffff0000, v116
	v_pk_add_f32 v[106:107], v[106:107], v[114:115]
	v_lshlrev_b32_e32 v114, 16, v117
	v_and_b32_e32 v115, 0xffff0000, v117
	v_pk_add_f32 v[102:103], v[102:103], v[118:119]
	v_pk_add_f32 v[108:109], v[108:109], v[114:115]

; #define GAS __attribute__((address_space(1)))
;     __device__ __forceinline__ void operator()(const f32x4 (&acc)[2][2][4][2], const Unit& u, int wr, int wc, int fr_, int fq_) const {
;     ...
;                 for (int m = 0; m < 4; ++m) { const int row = row0 + ai * HALF + m * 16;
;                     float sc = 1.f; if constexpr (MODE == EP_Q || MODE == EP_KV) sc = ((const GAS float*)rs)[row]; if constexpr (MODE == EP_GATE) { if (u.pn < 12) sc = ((const GAS float*)rs2)[row]; }
;                     if constexpr (MODE == EP_G2) { if (kind == 0) sc = ((const GAS float*)rs)[row]; else if (kind == 1) sc = ((const GAS float*)rs2)[row]; }
; #pragma unroll
;                     for (int bj = 0; bj < 2; ++bj) { const int col = colt + bj * HALF; f32x4 v0 = acc[ai][bj][m][0] * sc, v1 = acc[ai][bj][m][1] * sc;
;                         if constexpr (MODE == EP_STORE) { *(GAS u32x4*)(O + (size_t)row * ldc + col) = pack8(v0, v1); }
;                         else if constexpr (MODE == EP_BR) {
;                             ((GAS u32x4*)O)[((size_t)((((pm * 12 + u.pn) * 2 + ai) * 4 + m) * 2 + bj)) * 512 + wv_ * 64 + ln_] = pack8(v0, v1); }
;                         else if constexpr (MODE == EP_Q) { *(GAS u32x4*)(O + (size_t)row * ldc + col) = pack8(v0, v1); }
;                         else if constexpr (MODE == EP_G2) {
;                             if (kind == 0) *(GAS u32x4*)(O + (size_t)row * QW + col) = pack8(v0, v1);
;                             else if (kind == 1) { if (col < 512) *(GAS u32x4*)(O2 + (size_t)row * QW + (col >> 6) * QKD + (col & 63)) = pack8(v0, v1); else *(GAS u32x4*)(O3 + (size_t)row * VW + (col - 512)) = pack8(v0, v1); }
;                             else *(GAS u32x4*)(O4 + (size_t)row * 512 + col) = pack8(v0, v1); }
;                         else if constexpr (MODE == EP_KV) {
;                             if (col < 512) *(GAS u32x4*)(O + (size_t)row * QW + (col >> 6) * QKD + (col & 63)) = pack8(v0, v1);
;                             else *(GAS u32x4*)(O2 + (size_t)row * VW + (col - 512)) = pack8(v0, v1); }
;                         else if constexpr (MODE == EP_GATE) {
;                             GAS u32x4* brs = (GAS u32x4*)O2 + ((size_t)((ai * 4 + m) * 2 + bj)) * 512 + wv_ * 64 + ln_;
;                             if (u.pn >= 12) { *brs = pack8(v0, v1); continue; }
;                             const int n = u.pn >> 2, d = col - n * 1024;
.LBB0_999:
	s_nop 1
	v_mov_b32_e32 v82, v198
.LBB0_1000:
	v_or_b32_e32 v80, 48, v146
	v_ashrrev_i32_e32 v81, 31, v80
	v_pk_mul_f32 v[78:79], v[78:79], v[82:83] op_sel_hi:[1,0]
	v_pk_mul_f32 v[84:85], v[76:77], v[82:83] op_sel_hi:[1,0]
	v_pk_mul_f32 v[74:75], v[74:75], v[82:83] op_sel_hi:[1,0]
	v_pk_mul_f32 v[76:77], v[72:73], v[82:83] op_sel_hi:[1,0]
	v_lshl_add_u64 v[72:73], v[144:145], 4, s[18:19]
	s_and_b64 vcc, exec, s[44:45]
	s_mov_b64 s[76:77], -1
	s_cbranch_vccnz .LBB0_1008
	v_lshl_add_u64 v[86:87], v[142:143], 2, s[56:57]
	global_load_dwordx4 v[90:93], v[86:87], off offset:16
	s_nop 0
	global_load_dwordx4 v[86:89], v[86:87], off
	s_nop 0
	global_load_dwordx4 v[94:97], v[72:73], off
	s_or_b32 s76, s84, 6
	s_ashr_i32 s77, s76, 31
	s_lshl_b64 s[58:59], s[76:77], 13
	s_add_u32 s58, s5, s58
	s_addc_u32 s59, s60, s59
	s_and_b64 vcc, exec, s[42:43]
	s_waitcnt vmcnt(1)
	v_add_f32_e32 v83, v84, v86
	v_mul_f32_e32 v83, 0xbfb8aa3b, v83
	v_exp_f32_e32 v83, v83
	s_waitcnt vmcnt(0)
	v_lshlrev_b32_e32 v98, 16, v94
	v_and_b32_e32 v99, 0xffff0000, v94
	v_lshlrev_b32_e32 v94, 16, v95
	v_add_f32_e32 v83, 1.0, v83
	v_rcp_f32_e32 v86, v83
	v_add_f32_e32 v83, v85, v87
	v_mul_f32_e32 v83, 0xbfb8aa3b, v83
	v_exp_f32_e32 v83, v83
	v_and_b32_e32 v95, 0xffff0000, v95
	v_add_f32_e32 v83, 1.0, v83
	v_rcp_f32_e32 v87, v83
	v_add_f32_e32 v83, v78, v88
	v_mul_f32_e32 v83, 0xbfb8aa3b, v83
	v_exp_f32_e32 v83, v83
	v_pk_mul_f32 v[86:87], v[86:87], v[98:99]
	v_add_f32_e32 v83, 1.0, v83
	v_rcp_f32_e32 v88, v83
	v_add_f32_e32 v83, v79, v89
	v_mul_f32_e32 v83, 0xbfb8aa3b, v83
	v_exp_f32_e32 v83, v83
	s_nop 0
	v_add_f32_e32 v83, 1.0, v83
	v_rcp_f32_e32 v89, v83
	v_add_f32_e32 v83, v76, v90
	v_mul_f32_e32 v83, 0xbfb8aa3b, v83
	v_exp_f32_e32 v83, v83
	v_pk_mul_f32 v[88:89], v[88:89], v[94:95]
	v_lshlrev_b32_e32 v94, 16, v96
	v_and_b32_e32 v95, 0xffff0000, v96
	v_add_f32_e32 v83, 1.0, v83
	v_rcp_f32_e32 v90, v83
	v_add_f32_e32 v83, v77, v91
	v_mul_f32_e32 v83, 0xbfb8aa3b, v83
	v_exp_f32_e32 v83, v83
	s_nop 0
	v_add_f32_e32 v83, 1.0, v83
	v_rcp_f32_e32 v91, v83
	v_add_f32_e32 v83, v74, v92
	v_mul_f32_e32 v83, 0xbfb8aa3b, v83
	v_exp_f32_e32 v83, v83
	v_pk_mul_f32 v[90:91], v[90:91], v[94:95]
	v_lshlrev_b32_e32 v94, 16, v97
	v_and_b32_e32 v95, 0xffff0000, v97
	v_add_f32_e32 v83, 1.0, v83
	v_rcp_f32_e32 v92, v83
	v_add_f32_e32 v83, v75, v93
	v_mul_f32_e32 v83, 0xbfb8aa3b, v83
	v_exp_f32_e32 v83, v83
	s_nop 0
	v_add_f32_e32 v83, 1.0, v83
	v_rcp_f32_e32 v93, v83
	s_nop 0
	v_pk_mul_f32 v[92:93], v[92:93], v[94:95]
	v_lshl_add_u64 v[94:95], v[144:145], 4, s[58:59]
	s_cbranch_vccnz .LBB0_1003
	global_load_dwordx4 v[96:99], v[94:95], off
	s_waitcnt vmcnt(0)
	v_lshlrev_b32_e32 v100, 16, v96
	v_and_b32_e32 v101, 0xffff0000, v96
	v_lshlrev_b32_e32 v96, 16, v97
	v_and_b32_e32 v97, 0xffff0000, v97
	v_pk_add_f32 v[88:89], v[88:89], v[96:97]
	v_lshlrev_b32_e32 v96, 16, v98
	v_and_b32_e32 v97, 0xffff0000, v98
	v_pk_add_f32 v[90:91], v[90:91], v[96:97]
	v_lshlrev_b32_e32 v96, 16, v99
	v_and_b32_e32 v97, 0xffff0000, v99
	v_pk_add_f32 v[86:87], v[86:87], v[100:101]
	v_pk_add_f32 v[92:93], v[92:93], v[96:97]

; #define GAS __attribute__((address_space(1)))
;     __device__ __forceinline__ void operator()(const f32x4 (&acc)[2][2][4][2], const Unit& u, int wr, int wc, int fr_, int fq_) const {
;     ...
;                 for (int m = 0; m < 4; ++m) { const int row = row0 + ai * HALF + m * 16;
;                     float sc = 1.f; if constexpr (MODE == EP_Q || MODE == EP_KV) sc = ((const GAS float*)rs)[row]; if constexpr (MODE == EP_GATE) { if (u.pn < 12) sc = ((const GAS float*)rs2)[row]; }
;                     if constexpr (MODE == EP_G2) { if (kind == 0) sc = ((const GAS float*)rs)[row]; else if (kind == 1) sc = ((const GAS float*)rs2)[row]; }
; #pragma unroll
;                     for (int bj = 0; bj < 2; ++bj) { const int col = colt + bj * HALF; f32x4 v0 = acc[ai][bj][m][0] * sc, v1 = acc[ai][bj][m][1] * sc;
;                         if constexpr (MODE == EP_STORE) { *(GAS u32x4*)(O + (size_t)row * ldc + col) = pack8(v0, v1); }
;                         else if constexpr (MODE == EP_BR) {
;                             ((GAS u32x4*)O)[((size_t)((((pm * 12 + u.pn) * 2 + ai) * 4 + m) * 2 + bj)) * 512 + wv_ * 64 + ln_] = pack8(v0, v1); }
;                         else if constexpr (MODE == EP_Q) { *(GAS u32x4*)(O + (size_t)row * ldc + col) = pack8(v0, v1); }
;                         else if constexpr (MODE == EP_G2) {
;                             if (kind == 0) *(GAS u32x4*)(O + (size_t)row * QW + col) = pack8(v0, v1);
;                             else if (kind == 1) { if (col < 512) *(GAS u32x4*)(O2 + (size_t)row * QW + (col >> 6) * QKD + (col & 63)) = pack8(v0, v1); else *(GAS u32x4*)(O3 + (size_t)row * VW + (col - 512)) = pack8(v0, v1); }
;                             else *(GAS u32x4*)(O4 + (size_t)row * 512 + col) = pack8(v0, v1); }
;                         else if constexpr (MODE == EP_KV) {
;                             if (col < 512) *(GAS u32x4*)(O + (size_t)row * QW + (col >> 6) * QKD + (col & 63)) = pack8(v0, v1);
;                             else *(GAS u32x4*)(O2 + (size_t)row * VW + (col - 512)) = pack8(v0, v1); }
;                         else if constexpr (MODE == EP_GATE) {
;                             GAS u32x4* brs = (GAS u32x4*)O2 + ((size_t)((ai * 4 + m) * 2 + bj)) * 512 + wv_ * 64 + ln_;
;                             if (u.pn >= 12) { *brs = pack8(v0, v1); continue; }
;                             const int n = u.pn >> 2, d = col - n * 1024;
.LBB0_1019:
	s_nop 1
	v_mov_b32_e32 v66, v199
.LBB0_1020:
	v_add_u32_e32 v64, 0x80, v146
	v_ashrrev_i32_e32 v65, 31, v64
	v_pk_mul_f32 v[62:63], v[62:63], v[66:67] op_sel_hi:[1,0]
	v_pk_mul_f32 v[68:69], v[60:61], v[66:67] op_sel_hi:[1,0]
	v_pk_mul_f32 v[58:59], v[58:59], v[66:67] op_sel_hi:[1,0]
	v_pk_mul_f32 v[60:61], v[56:57], v[66:67] op_sel_hi:[1,0]
	v_lshl_add_u64 v[56:57], v[144:145], 4, s[14:15]
	s_and_b64 vcc, exec, s[44:45]
	s_mov_b64 s[76:77], -1
	s_cbranch_vccnz .LBB0_1028
	v_lshl_add_u64 v[70:71], v[142:143], 2, s[56:57]
	global_load_dwordx4 v[74:77], v[70:71], off offset:16
	s_nop 0
	global_load_dwordx4 v[70:73], v[70:71], off
	s_nop 0
	global_load_dwordx4 v[78:81], v[56:57], off
	s_or_b32 s76, s84, 8
	s_ashr_i32 s77, s76, 31
	s_lshl_b64 s[58:59], s[76:77], 13
	s_add_u32 s58, s5, s58
	s_addc_u32 s59, s60, s59
	s_and_b64 vcc, exec, s[42:43]
	s_waitcnt vmcnt(1)
	v_add_f32_e32 v67, v68, v70
	v_mul_f32_e32 v67, 0xbfb8aa3b, v67
	v_exp_f32_e32 v67, v67
	s_waitcnt vmcnt(0)
	v_lshlrev_b32_e32 v82, 16, v78
	v_and_b32_e32 v83, 0xffff0000, v78
	v_lshlrev_b32_e32 v78, 16, v79
	v_add_f32_e32 v67, 1.0, v67
	v_rcp_f32_e32 v70, v67
	v_add_f32_e32 v67, v69, v71
	v_mul_f32_e32 v67, 0xbfb8aa3b, v67
	v_exp_f32_e32 v67, v67
	v_and_b32_e32 v79, 0xffff0000, v79
	v_add_f32_e32 v67, 1.0, v67
	v_rcp_f32_e32 v71, v67
	v_add_f32_e32 v67, v62, v72
	v_mul_f32_e32 v67, 0xbfb8aa3b, v67
	v_exp_f32_e32 v67, v67
	v_pk_mul_f32 v[70:71], v[70:71], v[82:83]
	v_add_f32_e32 v67, 1.0, v67
	v_rcp_f32_e32 v72, v67
	v_add_f32_e32 v67, v63, v73
	v_mul_f32_e32 v67, 0xbfb8aa3b, v67
	v_exp_f32_e32 v67, v67
	s_nop 0
	v_add_f32_e32 v67, 1.0, v67
	v_rcp_f32_e32 v73, v67
	v_add_f32_e32 v67, v60, v74
	v_mul_f32_e32 v67, 0xbfb8aa3b, v67
	v_exp_f32_e32 v67, v67
	v_pk_mul_f32 v[72:73], v[72:73], v[78:79]
	v_lshlrev_b32_e32 v78, 16, v80
	v_and_b32_e32 v79, 0xffff0000, v80
	v_add_f32_e32 v67, 1.0, v67
	v_rcp_f32_e32 v74, v67
	v_add_f32_e32 v67, v61, v75
	v_mul_f32_e32 v67, 0xbfb8aa3b, v67
	v_exp_f32_e32 v67, v67
	s_nop 0
	v_add_f32_e32 v67, 1.0, v67
	v_rcp_f32_e32 v75, v67
	v_add_f32_e32 v67, v58, v76
	v_mul_f32_e32 v67, 0xbfb8aa3b, v67
	v_exp_f32_e32 v67, v67
	v_pk_mul_f32 v[74:75], v[74:75], v[78:79]
	v_lshlrev_b32_e32 v78, 16, v81
	v_and_b32_e32 v79, 0xffff0000, v81
	v_add_f32_e32 v67, 1.0, v67
	v_rcp_f32_e32 v76, v67
	v_add_f32_e32 v67, v59, v77
	v_mul_f32_e32 v67, 0xbfb8aa3b, v67
	v_exp_f32_e32 v67, v67
	s_nop 0
	v_add_f32_e32 v67, 1.0, v67
	v_rcp_f32_e32 v77, v67
	s_nop 0
	v_pk_mul_f32 v[76:77], v[76:77], v[78:79]
	v_lshl_add_u64 v[78:79], v[144:145], 4, s[58:59]
	s_cbranch_vccnz .LBB0_1023
	global_load_dwordx4 v[80:83], v[78:79], off
	s_waitcnt vmcnt(0)
	v_lshlrev_b32_e32 v84, 16, v80
	v_and_b32_e32 v85, 0xffff0000, v80
	v_lshlrev_b32_e32 v80, 16, v81
	v_and_b32_e32 v81, 0xffff0000, v81
	v_pk_add_f32 v[72:73], v[72:73], v[80:81]
	v_lshlrev_b32_e32 v80, 16, v82
	v_and_b32_e32 v81, 0xffff0000, v82
	v_pk_add_f32 v[74:75], v[74:75], v[80:81]
	v_lshlrev_b32_e32 v80, 16, v83
	v_and_b32_e32 v81, 0xffff0000, v83
	v_pk_add_f32 v[70:71], v[70:71], v[84:85]
	v_pk_add_f32 v[76:77], v[76:77], v[80:81]

; #define GAS __attribute__((address_space(1)))
;     __device__ __forceinline__ void operator()(const f32x4 (&acc)[2][2][4][2], const Unit& u, int wr, int wc, int fr_, int fq_) const {
;     ...
;                 for (int m = 0; m < 4; ++m) { const int row = row0 + ai * HALF + m * 16;
;                     float sc = 1.f; if constexpr (MODE == EP_Q || MODE == EP_KV) sc = ((const GAS float*)rs)[row]; if constexpr (MODE == EP_GATE) { if (u.pn < 12) sc = ((const GAS float*)rs2)[row]; }
;                     if constexpr (MODE == EP_G2) { if (kind == 0) sc = ((const GAS float*)rs)[row]; else if (kind == 1) sc = ((const GAS float*)rs2)[row]; }
; #pragma unroll
;                     for (int bj = 0; bj < 2; ++bj) { const int col = colt + bj * HALF; f32x4 v0 = acc[ai][bj][m][0] * sc, v1 = acc[ai][bj][m][1] * sc;
;                         if constexpr (MODE == EP_STORE) { *(GAS u32x4*)(O + (size_t)row * ldc + col) = pack8(v0, v1); }
;                         else if constexpr (MODE == EP_BR) {
;                             ((GAS u32x4*)O)[((size_t)((((pm * 12 + u.pn) * 2 + ai) * 4 + m) * 2 + bj)) * 512 + wv_ * 64 + ln_] = pack8(v0, v1); }
;                         else if constexpr (MODE == EP_Q) { *(GAS u32x4*)(O + (size_t)row * ldc + col) = pack8(v0, v1); }
;                         else if constexpr (MODE == EP_G2) {
;                             if (kind == 0) *(GAS u32x4*)(O + (size_t)row * QW + col) = pack8(v0, v1);
;                             else if (kind == 1) { if (col < 512) *(GAS u32x4*)(O2 + (size_t)row * QW + (col >> 6) * QKD + (col & 63)) = pack8(v0, v1); else *(GAS u32x4*)(O3 + (size_t)row * VW + (col - 512)) = pack8(v0, v1); }
;                             else *(GAS u32x4*)(O4 + (size_t)row * 512 + col) = pack8(v0, v1); }
;                         else if constexpr (MODE == EP_KV) {
;                             if (col < 512) *(GAS u32x4*)(O + (size_t)row * QW + (col >> 6) * QKD + (col & 63)) = pack8(v0, v1);
;                             else *(GAS u32x4*)(O2 + (size_t)row * VW + (col - 512)) = pack8(v0, v1); }
;                         else if constexpr (MODE == EP_GATE) {
;                             GAS u32x4* brs = (GAS u32x4*)O2 + ((size_t)((ai * 4 + m) * 2 + bj)) * 512 + wv_ * 64 + ln_;
;                             if (u.pn >= 12) { *brs = pack8(v0, v1); continue; }
;                             const int n = u.pn >> 2, d = col - n * 1024;
.LBB0_1039:
	s_nop 1
	v_mov_b32_e32 v50, v200
.LBB0_1040:
	v_add_u32_e32 v48, 0x90, v146
	v_ashrrev_i32_e32 v49, 31, v48
	v_pk_mul_f32 v[46:47], v[46:47], v[50:51] op_sel_hi:[1,0]
	v_pk_mul_f32 v[52:53], v[44:45], v[50:51] op_sel_hi:[1,0]
	v_pk_mul_f32 v[42:43], v[42:43], v[50:51] op_sel_hi:[1,0]
	v_pk_mul_f32 v[44:45], v[40:41], v[50:51] op_sel_hi:[1,0]
	v_lshl_add_u64 v[40:41], v[144:145], 4, s[2:3]
	s_and_b64 vcc, exec, s[44:45]
	s_mov_b64 s[76:77], -1
	s_cbranch_vccnz .LBB0_1048
	v_lshl_add_u64 v[54:55], v[142:143], 2, s[56:57]
	global_load_dwordx4 v[58:61], v[54:55], off offset:16
	s_nop 0
	global_load_dwordx4 v[54:57], v[54:55], off
	s_nop 0
	global_load_dwordx4 v[62:65], v[40:41], off
	s_or_b32 s76, s84, 10
	s_ashr_i32 s77, s76, 31
	s_lshl_b64 s[58:59], s[76:77], 13
	s_add_u32 s58, s5, s58
	s_addc_u32 s59, s60, s59
	s_and_b64 vcc, exec, s[42:43]
	s_waitcnt vmcnt(1)
	v_add_f32_e32 v51, v52, v54
	v_mul_f32_e32 v51, 0xbfb8aa3b, v51
	v_exp_f32_e32 v51, v51
	s_waitcnt vmcnt(0)
	v_lshlrev_b32_e32 v66, 16, v62
	v_and_b32_e32 v67, 0xffff0000, v62
	v_lshlrev_b32_e32 v62, 16, v63
	v_add_f32_e32 v51, 1.0, v51
	v_rcp_f32_e32 v54, v51
	v_add_f32_e32 v51, v53, v55
	v_mul_f32_e32 v51, 0xbfb8aa3b, v51
	v_exp_f32_e32 v51, v51
	v_and_b32_e32 v63, 0xffff0000, v63
	v_add_f32_e32 v51, 1.0, v51
	v_rcp_f32_e32 v55, v51
	v_add_f32_e32 v51, v46, v56
	v_mul_f32_e32 v51, 0xbfb8aa3b, v51
	v_exp_f32_e32 v51, v51
	v_pk_mul_f32 v[54:55], v[54:55], v[66:67]
	v_add_f32_e32 v51, 1.0, v51
	v_rcp_f32_e32 v56, v51
	v_add_f32_e32 v51, v47, v57
	v_mul_f32_e32 v51, 0xbfb8aa3b, v51
	v_exp_f32_e32 v51, v51
	s_nop 0
	v_add_f32_e32 v51, 1.0, v51
	v_rcp_f32_e32 v57, v51
	v_add_f32_e32 v51, v44, v58
	v_mul_f32_e32 v51, 0xbfb8aa3b, v51
	v_exp_f32_e32 v51, v51
	v_pk_mul_f32 v[56:57], v[56:57], v[62:63]
	v_lshlrev_b32_e32 v62, 16, v64
	v_and_b32_e32 v63, 0xffff0000, v64
	v_add_f32_e32 v51, 1.0, v51
	v_rcp_f32_e32 v58, v51
	v_add_f32_e32 v51, v45, v59
	v_mul_f32_e32 v51, 0xbfb8aa3b, v51
	v_exp_f32_e32 v51, v51
	s_nop 0
	v_add_f32_e32 v51, 1.0, v51
	v_rcp_f32_e32 v59, v51
	v_add_f32_e32 v51, v42, v60
	v_mul_f32_e32 v51, 0xbfb8aa3b, v51
	v_exp_f32_e32 v51, v51
	v_pk_mul_f32 v[58:59], v[58:59], v[62:63]
	v_lshlrev_b32_e32 v62, 16, v65
	v_and_b32_e32 v63, 0xffff0000, v65
	v_add_f32_e32 v51, 1.0, v51
	v_rcp_f32_e32 v60, v51
	v_add_f32_e32 v51, v43, v61
	v_mul_f32_e32 v51, 0xbfb8aa3b, v51
	v_exp_f32_e32 v51, v51
	s_nop 0
	v_add_f32_e32 v51, 1.0, v51
	v_rcp_f32_e32 v61, v51
	s_nop 0
	v_pk_mul_f32 v[60:61], v[60:61], v[62:63]
	v_lshl_add_u64 v[62:63], v[144:145], 4, s[58:59]
	s_cbranch_vccnz .LBB0_1043
	global_load_dwordx4 v[64:67], v[62:63], off
	s_waitcnt vmcnt(0)
	v_lshlrev_b32_e32 v68, 16, v64
	v_and_b32_e32 v69, 0xffff0000, v64
	v_lshlrev_b32_e32 v64, 16, v65
	v_and_b32_e32 v65, 0xffff0000, v65
	v_pk_add_f32 v[56:57], v[56:57], v[64:65]
	v_lshlrev_b32_e32 v64, 16, v66
	v_and_b32_e32 v65, 0xffff0000, v66
	v_pk_add_f32 v[58:59], v[58:59], v[64:65]
	v_lshlrev_b32_e32 v64, 16, v67
	v_and_b32_e32 v65, 0xffff0000, v67
	v_pk_add_f32 v[54:55], v[54:55], v[68:69]
	v_pk_add_f32 v[60:61], v[60:61], v[64:65]

; #define GAS __attribute__((address_space(1)))
;     __device__ __forceinline__ void operator()(const f32x4 (&acc)[2][2][4][2], const Unit& u, int wr, int wc, int fr_, int fq_) const {
;     ...
;                 for (int m = 0; m < 4; ++m) { const int row = row0 + ai * HALF + m * 16;
;                     float sc = 1.f; if constexpr (MODE == EP_Q || MODE == EP_KV) sc = ((const GAS float*)rs)[row]; if constexpr (MODE == EP_GATE) { if (u.pn < 12) sc = ((const GAS float*)rs2)[row]; }
;                     if constexpr (MODE == EP_G2) { if (kind == 0) sc = ((const GAS float*)rs)[row]; else if (kind == 1) sc = ((const GAS float*)rs2)[row]; }
; #pragma unroll
;                     for (int bj = 0; bj < 2; ++bj) { const int col = colt + bj * HALF; f32x4 v0 = acc[ai][bj][m][0] * sc, v1 = acc[ai][bj][m][1] * sc;
;                         if constexpr (MODE == EP_STORE) { *(GAS u32x4*)(O + (size_t)row * ldc + col) = pack8(v0, v1); }
;                         else if constexpr (MODE == EP_BR) {
;                             ((GAS u32x4*)O)[((size_t)((((pm * 12 + u.pn) * 2 + ai) * 4 + m) * 2 + bj)) * 512 + wv_ * 64 + ln_] = pack8(v0, v1); }
;                         else if constexpr (MODE == EP_Q) { *(GAS u32x4*)(O + (size_t)row * ldc + col) = pack8(v0, v1); }
;                         else if constexpr (MODE == EP_G2) {
;                             if (kind == 0) *(GAS u32x4*)(O + (size_t)row * QW + col) = pack8(v0, v1);
;                             else if (kind == 1) { if (col < 512) *(GAS u32x4*)(O2 + (size_t)row * QW + (col >> 6) * QKD + (col & 63)) = pack8(v0, v1); else *(GAS u32x4*)(O3 + (size_t)row * VW + (col - 512)) = pack8(v0, v1); }
;                             else *(GAS u32x4*)(O4 + (size_t)row * 512 + col) = pack8(v0, v1); }
;                         else if constexpr (MODE == EP_KV) {
;                             if (col < 512) *(GAS u32x4*)(O + (size_t)row * QW + (col >> 6) * QKD + (col & 63)) = pack8(v0, v1);
;                             else *(GAS u32x4*)(O2 + (size_t)row * VW + (col - 512)) = pack8(v0, v1); }
;                         else if constexpr (MODE == EP_GATE) {
;                             GAS u32x4* brs = (GAS u32x4*)O2 + ((size_t)((ai * 4 + m) * 2 + bj)) * 512 + wv_ * 64 + ln_;
;                             if (u.pn >= 12) { *brs = pack8(v0, v1); continue; }
;                             const int n = u.pn >> 2, d = col - n * 1024;
.LBB0_1059:
	s_nop 1
	v_mov_b32_e32 v34, v201
.LBB0_1060:
	v_add_u32_e32 v32, 0xa0, v146
	v_ashrrev_i32_e32 v33, 31, v32
	v_pk_mul_f32 v[30:31], v[30:31], v[34:35] op_sel_hi:[1,0]
	v_pk_mul_f32 v[36:37], v[28:29], v[34:35] op_sel_hi:[1,0]
	v_pk_mul_f32 v[26:27], v[26:27], v[34:35] op_sel_hi:[1,0]
	v_pk_mul_f32 v[28:29], v[24:25], v[34:35] op_sel_hi:[1,0]
	v_lshl_add_u64 v[24:25], v[144:145], 4, s[22:23]
	s_and_b64 vcc, exec, s[44:45]
	s_mov_b64 s[76:77], -1
	s_cbranch_vccnz .LBB0_1068
	v_lshl_add_u64 v[38:39], v[142:143], 2, s[56:57]
	global_load_dwordx4 v[42:45], v[38:39], off offset:16
	s_nop 0
	global_load_dwordx4 v[38:41], v[38:39], off
	s_nop 0
	global_load_dwordx4 v[46:49], v[24:25], off
	s_or_b32 s76, s84, 12
	s_ashr_i32 s77, s76, 31
	s_lshl_b64 s[58:59], s[76:77], 13
	s_add_u32 s58, s5, s58
	s_addc_u32 s59, s60, s59
	s_and_b64 vcc, exec, s[42:43]
	s_waitcnt vmcnt(1)
	v_add_f32_e32 v35, v36, v38
	v_mul_f32_e32 v35, 0xbfb8aa3b, v35
	v_exp_f32_e32 v35, v35
	s_waitcnt vmcnt(0)
	v_lshlrev_b32_e32 v50, 16, v46
	v_and_b32_e32 v51, 0xffff0000, v46
	v_lshlrev_b32_e32 v46, 16, v47
	v_add_f32_e32 v35, 1.0, v35
	v_rcp_f32_e32 v38, v35
	v_add_f32_e32 v35, v37, v39
	v_mul_f32_e32 v35, 0xbfb8aa3b, v35
	v_exp_f32_e32 v35, v35
	v_and_b32_e32 v47, 0xffff0000, v47
	v_add_f32_e32 v35, 1.0, v35
	v_rcp_f32_e32 v39, v35
	v_add_f32_e32 v35, v30, v40
	v_mul_f32_e32 v35, 0xbfb8aa3b, v35
	v_exp_f32_e32 v35, v35
	v_pk_mul_f32 v[38:39], v[38:39], v[50:51]
	v_add_f32_e32 v35, 1.0, v35
	v_rcp_f32_e32 v40, v35
	v_add_f32_e32 v35, v31, v41
	v_mul_f32_e32 v35, 0xbfb8aa3b, v35
	v_exp_f32_e32 v35, v35
	s_nop 0
	v_add_f32_e32 v35, 1.0, v35
	v_rcp_f32_e32 v41, v35
	v_add_f32_e32 v35, v28, v42
	v_mul_f32_e32 v35, 0xbfb8aa3b, v35
	v_exp_f32_e32 v35, v35
	v_pk_mul_f32 v[40:41], v[40:41], v[46:47]
	v_lshlrev_b32_e32 v46, 16, v48
	v_and_b32_e32 v47, 0xffff0000, v48
	v_add_f32_e32 v35, 1.0, v35
	v_rcp_f32_e32 v42, v35
	v_add_f32_e32 v35, v29, v43
	v_mul_f32_e32 v35, 0xbfb8aa3b, v35
	v_exp_f32_e32 v35, v35
	s_nop 0
	v_add_f32_e32 v35, 1.0, v35
	v_rcp_f32_e32 v43, v35
	v_add_f32_e32 v35, v26, v44
	v_mul_f32_e32 v35, 0xbfb8aa3b, v35
	v_exp_f32_e32 v35, v35
	v_pk_mul_f32 v[42:43], v[42:43], v[46:47]
	v_lshlrev_b32_e32 v46, 16, v49
	v_and_b32_e32 v47, 0xffff0000, v49
	v_add_f32_e32 v35, 1.0, v35
	v_rcp_f32_e32 v44, v35
	v_add_f32_e32 v35, v27, v45
	v_mul_f32_e32 v35, 0xbfb8aa3b, v35
	v_exp_f32_e32 v35, v35
	s_nop 0
	v_add_f32_e32 v35, 1.0, v35
	v_rcp_f32_e32 v45, v35
	s_nop 0
	v_pk_mul_f32 v[44:45], v[44:45], v[46:47]
	v_lshl_add_u64 v[46:47], v[144:145], 4, s[58:59]
	s_cbranch_vccnz .LBB0_1063
	global_load_dwordx4 v[48:51], v[46:47], off
	s_waitcnt vmcnt(0)
	v_lshlrev_b32_e32 v52, 16, v48
	v_and_b32_e32 v53, 0xffff0000, v48
	v_lshlrev_b32_e32 v48, 16, v49
	v_and_b32_e32 v49, 0xffff0000, v49
	v_pk_add_f32 v[40:41], v[40:41], v[48:49]
	v_lshlrev_b32_e32 v48, 16, v50
	v_and_b32_e32 v49, 0xffff0000, v50
	v_pk_add_f32 v[42:43], v[42:43], v[48:49]
	v_lshlrev_b32_e32 v48, 16, v51
	v_and_b32_e32 v49, 0xffff0000, v51
	v_pk_add_f32 v[38:39], v[38:39], v[52:53]
	v_pk_add_f32 v[44:45], v[44:45], v[48:49]

; #define GAS __attribute__((address_space(1)))
;     __device__ __forceinline__ void operator()(const f32x4 (&acc)[2][2][4][2], const Unit& u, int wr, int wc, int fr_, int fq_) const {
;     ...
;                 for (int m = 0; m < 4; ++m) { const int row = row0 + ai * HALF + m * 16;
;                     float sc = 1.f; if constexpr (MODE == EP_Q || MODE == EP_KV) sc = ((const GAS float*)rs)[row]; if constexpr (MODE == EP_GATE) { if (u.pn < 12) sc = ((const GAS float*)rs2)[row]; }
;                     if constexpr (MODE == EP_G2) { if (kind == 0) sc = ((const GAS float*)rs)[row]; else if (kind == 1) sc = ((const GAS float*)rs2)[row]; }
; #pragma unroll
;                     for (int bj = 0; bj < 2; ++bj) { const int col = colt + bj * HALF; f32x4 v0 = acc[ai][bj][m][0] * sc, v1 = acc[ai][bj][m][1] * sc;
;                         if constexpr (MODE == EP_STORE) { *(GAS u32x4*)(O + (size_t)row * ldc + col) = pack8(v0, v1); }
;                         else if constexpr (MODE == EP_BR) {
;                             ((GAS u32x4*)O)[((size_t)((((pm * 12 + u.pn) * 2 + ai) * 4 + m) * 2 + bj)) * 512 + wv_ * 64 + ln_] = pack8(v0, v1); }
;                         else if constexpr (MODE == EP_Q) { *(GAS u32x4*)(O + (size_t)row * ldc + col) = pack8(v0, v1); }
;                         else if constexpr (MODE == EP_G2) {
;                             if (kind == 0) *(GAS u32x4*)(O + (size_t)row * QW + col) = pack8(v0, v1);
;                             else if (kind == 1) { if (col < 512) *(GAS u32x4*)(O2 + (size_t)row * QW + (col >> 6) * QKD + (col & 63)) = pack8(v0, v1); else *(GAS u32x4*)(O3 + (size_t)row * VW + (col - 512)) = pack8(v0, v1); }
;                             else *(GAS u32x4*)(O4 + (size_t)row * 512 + col) = pack8(v0, v1); }
;                         else if constexpr (MODE == EP_KV) {
;                             if (col < 512) *(GAS u32x4*)(O + (size_t)row * QW + (col >> 6) * QKD + (col & 63)) = pack8(v0, v1);
;                             else *(GAS u32x4*)(O2 + (size_t)row * VW + (col - 512)) = pack8(v0, v1); }
;                         else if constexpr (MODE == EP_GATE) {
;                             GAS u32x4* brs = (GAS u32x4*)O2 + ((size_t)((ai * 4 + m) * 2 + bj)) * 512 + wv_ * 64 + ln_;
;                             if (u.pn >= 12) { *brs = pack8(v0, v1); continue; }
;                             const int n = u.pn >> 2, d = col - n * 1024;
.LBB0_1079:
	s_nop 1
	v_mov_b32_e32 v18, v202
.LBB0_1080:
	v_add_u32_e32 v16, 0xb0, v146
	v_ashrrev_i32_e32 v17, 31, v16
	v_pk_mul_f32 v[14:15], v[14:15], v[18:19] op_sel_hi:[1,0]
	v_pk_mul_f32 v[20:21], v[12:13], v[18:19] op_sel_hi:[1,0]
	v_pk_mul_f32 v[10:11], v[10:11], v[18:19] op_sel_hi:[1,0]
	v_pk_mul_f32 v[12:13], v[8:9], v[18:19] op_sel_hi:[1,0]
	v_lshl_add_u64 v[8:9], v[144:145], 4, s[30:31]
	s_and_b64 vcc, exec, s[44:45]
	s_mov_b64 s[46:47], -1
	s_cbranch_vccnz .LBB0_1088
	v_lshl_add_u64 v[22:23], v[142:143], 2, s[56:57]
	global_load_dwordx4 v[26:29], v[22:23], off offset:16
	s_nop 0
	global_load_dwordx4 v[22:25], v[22:23], off
	s_nop 0
	global_load_dwordx4 v[30:33], v[8:9], off
	s_or_b32 s46, s84, 14
	s_ashr_i32 s47, s46, 31
	s_lshl_b64 s[46:47], s[46:47], 13
	s_add_u32 s46, s5, s46
	s_addc_u32 s47, s60, s47
	s_and_b64 vcc, exec, s[42:43]
	s_waitcnt vmcnt(1)
	v_add_f32_e32 v19, v20, v22
	v_mul_f32_e32 v19, 0xbfb8aa3b, v19
	v_exp_f32_e32 v19, v19
	s_waitcnt vmcnt(0)
	v_lshlrev_b32_e32 v34, 16, v30
	v_and_b32_e32 v35, 0xffff0000, v30
	v_lshlrev_b32_e32 v30, 16, v31
	v_add_f32_e32 v19, 1.0, v19
	v_rcp_f32_e32 v22, v19
	v_add_f32_e32 v19, v21, v23
	v_mul_f32_e32 v19, 0xbfb8aa3b, v19
	v_exp_f32_e32 v19, v19
	v_and_b32_e32 v31, 0xffff0000, v31
	v_add_f32_e32 v19, 1.0, v19
	v_rcp_f32_e32 v23, v19
	v_add_f32_e32 v19, v14, v24
	v_mul_f32_e32 v19, 0xbfb8aa3b, v19
	v_exp_f32_e32 v19, v19
	v_pk_mul_f32 v[22:23], v[22:23], v[34:35]
	v_add_f32_e32 v19, 1.0, v19
	v_rcp_f32_e32 v24, v19
	v_add_f32_e32 v19, v15, v25
	v_mul_f32_e32 v19, 0xbfb8aa3b, v19
	v_exp_f32_e32 v19, v19
	s_nop 0
	v_add_f32_e32 v19, 1.0, v19
	v_rcp_f32_e32 v25, v19
	v_add_f32_e32 v19, v12, v26
	v_mul_f32_e32 v19, 0xbfb8aa3b, v19
	v_exp_f32_e32 v19, v19
	v_pk_mul_f32 v[24:25], v[24:25], v[30:31]
	v_lshlrev_b32_e32 v30, 16, v32
	v_and_b32_e32 v31, 0xffff0000, v32
	v_add_f32_e32 v19, 1.0, v19
	v_rcp_f32_e32 v26, v19
	v_add_f32_e32 v19, v13, v27
	v_mul_f32_e32 v19, 0xbfb8aa3b, v19
	v_exp_f32_e32 v19, v19
	s_nop 0
	v_add_f32_e32 v19, 1.0, v19
	v_rcp_f32_e32 v27, v19
	v_add_f32_e32 v19, v10, v28
	v_mul_f32_e32 v19, 0xbfb8aa3b, v19
	v_exp_f32_e32 v19, v19
	v_pk_mul_f32 v[26:27], v[26:27], v[30:31]
	v_lshlrev_b32_e32 v30, 16, v33
	v_and_b32_e32 v31, 0xffff0000, v33
	v_add_f32_e32 v19, 1.0, v19
	v_rcp_f32_e32 v28, v19
	v_add_f32_e32 v19, v11, v29
	v_mul_f32_e32 v19, 0xbfb8aa3b, v19
	v_exp_f32_e32 v19, v19
	s_nop 0
	v_add_f32_e32 v19, 1.0, v19
	v_rcp_f32_e32 v29, v19
	s_nop 0
	v_pk_mul_f32 v[28:29], v[28:29], v[30:31]
	v_lshl_add_u64 v[30:31], v[144:145], 4, s[46:47]
	s_cbranch_vccnz .LBB0_1083
	global_load_dwordx4 v[32:35], v[30:31], off
	s_waitcnt vmcnt(0)
	v_lshlrev_b32_e32 v36, 16, v32
	v_and_b32_e32 v37, 0xffff0000, v32
	v_lshlrev_b32_e32 v32, 16, v33
	v_and_b32_e32 v33, 0xffff0000, v33
	v_pk_add_f32 v[24:25], v[24:25], v[32:33]
	v_lshlrev_b32_e32 v32, 16, v34
	v_and_b32_e32 v33, 0xffff0000, v34
	v_pk_add_f32 v[26:27], v[26:27], v[32:33]
	v_lshlrev_b32_e32 v32, 16, v35
	v_and_b32_e32 v33, 0xffff0000, v35
	v_pk_add_f32 v[22:23], v[22:23], v[36:37]
	v_pk_add_f32 v[28:29], v[28:29], v[32:33]
